# MoBA bias: LDS positions prescaled x4, clamp folded into LUT address bounds, lsel mask via out-of-range LUT slot; 58 fewer VALU per tile-step
# speedup vs baseline: 1.0195x; 1.0170x over previous
; __global__ void __launch_bounds__(512) fwd_megakernel(KArgs a) {
;     ...
;     unsigned char* ws = a.ws;
;     float* ssq = (float*)(ws + WS_SSQ);
;     float* cosT = (float*)(ws + WS_COS); float* sinT = (float*)(ws + WS_SIN);
;     float* lutG = (float*)(ws + WS_LUT); float* kmeanG = (float*)(ws + WS_KMEAN);
;     bf16* XB = (bf16*)(ws + WS_XB);
;     ...
;     for (int layer = 0; layer < 4; ++layer) {
;         const int j = layer >> 1; const bool is_mla = (layer & 1) == 0;
;         float* ssq_attn = ssq + (size_t)SSQ_ATTN * TOK * 16; float* ssq_attn_next = ssq_attn; float* ssq_mlp = ssq + (size_t)SSQ_MLP * TOK * 16;
;         const bf16* Oattn; const bf16* Wo_t;
;         unsigned char* wbl = is_mla ? (ws + WS_WMLA + j * W_MLA_SZ) : (ws + WS_WMOBA + j * W_MOBA_SZ);
;         bf16* CQ = (bf16*)(ws + WS_CQ); bf16* CKV = (bf16*)(ws + WS_CKV); bf16* KPE = (bf16*)(ws + WS_KPE);
;         bf16* Q = (bf16*)(ws + WS_Q); bf16* KN = (bf16*)(ws + WS_KN); bf16* VRAW = (bf16*)(ws + WS_VRAW);
;         bf16* QKV = (bf16*)(ws + WS_QKV);
;         float* ssq_cq = ssq + (size_t)SSQ_CQ * TOK * 16; float* ssq_ckv = ssq + (size_t)SSQ_CKV * TOK * 16;
.LBB0_162:
	s_add_u32 s0, s68, 0x1f400000
	s_addc_u32 s1, s69, 0
	s_add_u32 s76, s68, 0x200000
	s_addc_u32 s77, s69, 0
	s_add_u32 s78, s68, 0x600000
	s_addc_u32 s79, s69, 0
	s_add_u32 s62, s68, 0xa00000
	s_addc_u32 s63, s69, 0
	s_add_u32 s66, s68, 0xa80000
	s_addc_u32 s67, s69, 0
	s_mov_b64 s[4:5], s[68:69]
	s_add_u32 s68, s4, 0x6800000
	v_writelane_b32 v252, s0, 30
	s_addc_u32 s69, s5, 0
	v_mov_b32_e32 v181, 0
	v_writelane_b32 v252, s1, 31
	s_add_u32 s0, s4, 0x1f600000
	s_addc_u32 s1, s5, 0
	v_writelane_b32 v252, s0, 32
	v_mov_b32_e32 v204, 0x358637bd
	v_mov_b32_e32 v205, 0x260
	v_writelane_b32 v252, s1, 33
	s_add_u32 s0, s4, 0x1cc00000
	s_addc_u32 s1, s5, 0
	v_writelane_b32 v252, s0, 34
	v_mov_b32_e32 v182, 0x43000000
	v_mbcnt_hi_u32_b32 v206, -1, v76
	v_writelane_b32 v252, s1, 35
	s_add_u32 s0, s4, 0x1e400000
	s_addc_u32 s1, s5, 0
	s_add_u32 s86, s4, 0x1c800000
	s_addc_u32 s87, s5, 0
	s_add_u32 s88, s4, 0xa800000
	s_addc_u32 s89, s5, 0
	s_add_u32 s90, s4, 0x10800000
	s_addc_u32 s91, s5, 0
	s_add_u32 s92, s4, 0x14800000
	v_writelane_b32 v252, s0, 36
	s_addc_u32 s93, s5, 0
	v_mov_b32_e32 v207, 0xff800000
	v_writelane_b32 v252, s1, 37
	s_add_u32 s0, s4, 0x1fa00000
	s_addc_u32 s1, s5, 0
	v_writelane_b32 v252, s0, 38
	v_mov_b32_e32 v208, 0x139fc
	v_mov_b32_e32 v209, 0xf149f2ca
	v_writelane_b32 v252, s1, 39
	s_add_u32 s0, s4, 0x1f800000
	s_addc_u32 s1, s5, 0
	v_writelane_b32 v252, s0, 40
	s_cmpk_lt_i32 s2, 0x180
	s_movk_i32 s36, 0x300
	v_writelane_b32 v252, s1, 41
	s_cselect_b64 s[0:1], -1, 0
	v_writelane_b32 v252, s0, 42
	s_ashr_i32 s3, s2, 31
	s_ashr_i32 s33, s84, 31
	v_writelane_b32 v252, s1, 43
	s_lshr_b32 s0, s3, 29
	s_add_i32 s0, s2, s0
	s_ashr_i32 s13, s0, 3
	s_and_b32 s0, s0, -8
	s_sub_i32 s14, s2, s0
	s_add_u32 s80, s4, 0xb00200
	s_addc_u32 s81, s5, 0
	s_add_u32 s16, s4, 0xb00400
	s_addc_u32 s17, s5, 0
	s_add_u32 s18, s4, 0xb00500
	s_addc_u32 s19, s5, 0
	s_add_u32 s64, s4, 0xb00600
	s_addc_u32 s65, s5, 0
	s_add_u32 s0, s4, 0xb00700
	s_addc_u32 s1, s5, 0
	v_writelane_b32 v252, s0, 44
	s_mov_b32 s51, 0
	s_mov_b64 s[58:59], 0x80
	v_writelane_b32 v252, s1, 45
	s_add_u32 s0, s4, 0xb00800
	s_addc_u32 s1, s5, 0
	v_writelane_b32 v252, s0, 46
	s_mov_b32 s94, 0x3dd53b94
	s_nop 0
	v_writelane_b32 v252, s1, 47
	s_add_u32 s0, s4, 0xb00900
	s_addc_u32 s1, s5, 0
	v_writelane_b32 v252, s0, 48
	s_nop 1
	v_writelane_b32 v252, s1, 49
	s_add_u32 s0, s4, 0xb00a00
	s_addc_u32 s1, s5, 0
	v_writelane_b32 v252, s0, 50
	s_nop 1
	v_writelane_b32 v252, s1, 51
	s_add_u32 s0, s4, 0xb00b00
	s_addc_u32 s1, s5, 0
	v_writelane_b32 v252, s0, 52
	s_nop 1
	v_writelane_b32 v252, s1, 53
	s_add_u32 s0, s4, 0xb00c00
	s_addc_u32 s1, s5, 0
	v_writelane_b32 v252, s0, 54
	s_nop 1
	v_writelane_b32 v252, s1, 55
	s_add_u32 s0, s4, 0xb00d00
	s_addc_u32 s1, s5, 0
	v_writelane_b32 v252, s0, 56
	s_nop 1
	v_writelane_b32 v252, s1, 57
	s_add_u32 s0, s4, 0xb00e00
	s_addc_u32 s1, s5, 0
	v_writelane_b32 v252, s0, 58
	s_nop 1
	v_writelane_b32 v252, s1, 59
	s_add_u32 s0, s4, 0xb00f00
	s_addc_u32 s1, s5, 0
	v_writelane_b32 v252, s0, 60
	s_nop 1
	v_writelane_b32 v252, s1, 61
	s_add_u32 s0, s4, 0xb01000
	s_addc_u32 s1, s5, 0
	v_writelane_b32 v252, s0, 62
	s_nop 1
	v_writelane_b32 v252, s1, 63
	s_add_u32 s0, s4, 0xb01100
	s_addc_u32 s1, s5, 0
	v_writelane_b32 v253, s0, 0
	s_nop 1
	v_writelane_b32 v253, s1, 1
	s_add_u32 s0, s4, 0xb01200
	s_addc_u32 s1, s5, 0
	v_writelane_b32 v253, s0, 2
	s_nop 1
	v_writelane_b32 v253, s1, 3
	s_add_u32 s0, s4, 0xb01300
	s_addc_u32 s1, s5, 0
	v_writelane_b32 v253, s0, 4
	s_cmp_eq_u32 s73, 15
	s_nop 0
	v_writelane_b32 v253, s1, 5
	s_cselect_b64 s[0:1], -1, 0
	v_writelane_b32 v253, s0, 6
	s_cmp_eq_u32 s73, 14
	s_nop 0
	v_writelane_b32 v253, s1, 7
	s_cselect_b64 s[0:1], -1, 0
	v_writelane_b32 v253, s0, 8
	s_cmp_eq_u32 s73, 13
	s_nop 0
	v_writelane_b32 v253, s1, 9
	s_cselect_b64 s[0:1], -1, 0
	v_writelane_b32 v253, s0, 10
	s_cmp_eq_u32 s73, 12
	s_nop 0
	v_writelane_b32 v253, s1, 11
	s_cselect_b64 s[0:1], -1, 0
	v_writelane_b32 v253, s0, 12
	s_cmp_eq_u32 s73, 11
	s_nop 0
	v_writelane_b32 v253, s1, 13
	s_cselect_b64 s[0:1], -1, 0
	v_writelane_b32 v253, s0, 14
	s_cmp_eq_u32 s73, 10
	s_nop 0
	v_writelane_b32 v253, s1, 15
	s_cselect_b64 s[0:1], -1, 0
	v_writelane_b32 v253, s0, 16
	s_cmp_eq_u32 s73, 9
	s_nop 0
	v_writelane_b32 v253, s1, 17
	s_cselect_b64 s[0:1], -1, 0
	v_writelane_b32 v253, s0, 18
	s_cmp_eq_u32 s73, 8
	s_nop 0
	v_writelane_b32 v253, s1, 19
	s_cselect_b64 s[0:1], -1, 0
	v_writelane_b32 v253, s0, 20
	s_cmp_eq_u32 s73, 7
	s_nop 0
	v_writelane_b32 v253, s1, 21
	s_cselect_b64 s[0:1], -1, 0
	v_writelane_b32 v253, s0, 22
	s_cmp_eq_u32 s73, 6
	s_nop 0
	v_writelane_b32 v253, s1, 23
	s_cselect_b64 s[0:1], -1, 0
	v_writelane_b32 v253, s0, 24
	s_cmp_eq_u32 s73, 5
	s_nop 0
	v_writelane_b32 v253, s1, 25
	s_cselect_b64 s[0:1], -1, 0
	v_writelane_b32 v253, s0, 26
	s_cmp_eq_u32 s73, 4
	s_nop 0
	v_writelane_b32 v253, s1, 27
	s_cselect_b64 s[0:1], -1, 0
	v_writelane_b32 v253, s0, 28
	s_cmp_eq_u32 s73, 3
	s_nop 0
	v_writelane_b32 v253, s1, 29
	s_cselect_b64 s[0:1], -1, 0
	v_writelane_b32 v253, s0, 30
	s_cmp_eq_u32 s73, 2
	s_nop 0
	v_writelane_b32 v253, s1, 31
	s_cselect_b64 s[0:1], -1, 0
	v_writelane_b32 v253, s0, 32
	s_cmp_eq_u32 s73, 1
	s_nop 0
	v_writelane_b32 v253, s1, 33
	s_cselect_b64 s[0:1], -1, 0
	v_writelane_b32 v253, s0, 34
	s_cmp_eq_u32 s73, 0
	s_nop 0
	v_writelane_b32 v253, s1, 35
	s_cselect_b64 s[0:1], -1, 0
	v_writelane_b32 v253, s0, 36
	s_nop 1
	v_writelane_b32 v253, s1, 37
	s_lshl_b32 s0, s73, 8
	s_add_u32 s0, s26, s0
	s_addc_u32 s1, s27, 0
	s_add_u32 s6, s0, 0x1400
	s_addc_u32 s7, s1, 0
	v_writelane_b32 v253, s6, 38
	s_add_u32 s0, s0, 0x2400
	s_addc_u32 s1, s1, 0
;     __host__ __device__ bool next(int i, Unit& u) const { const int nr = nwg / G; if (i >= nr) return false; return StaticOrder::next(nr - 1 - i, u); }
;     __host__ __device__ bool next(int i, Unit& u) const {
;         const long L = (long)i * G + c; if (L >= nwg) return false;
;         int wgid = (int)L; { const int q = nwg / NXCD, r = nwg % NXCD, xcd = wgid % NXCD, off = wgid / NXCD; wgid = (xcd < r ? xcd * (q + 1) : r * (q + 1) + (xcd - r) * q) + off; }
;         const int nig = WGM * nN, gid = wgid / nig, fm = gid * WGM, gsz = (nM - fm) < WGM ? (nM - fm) : WGM;
;         u.pm = fm + ((wgid % nig) % gsz); u.pn = (wgid % nig) / gsz; return true;
	v_writelane_b32 v253, s7, 39
	v_writelane_b32 v253, s0, 40
	s_nop 1
	v_writelane_b32 v253, s1, 41
	s_add_u32 s0, s4, 0xb03400
	s_addc_u32 s1, s5, 0
	v_writelane_b32 v253, s0, 42
	s_nop 1
	v_writelane_b32 v253, s1, 43
	s_add_u32 s0, s4, 0xb03500
	s_addc_u32 s1, s5, 0
	v_writelane_b32 v253, s0, 44
	s_nop 1
	v_writelane_b32 v253, s1, 45
	s_lshl_b32 s0, s70, 3
	s_cmpk_lt_i32 s70, 0x1000
	v_writelane_b32 v253, s0, 46
	s_cselect_b64 s[0:1], -1, 0
	v_writelane_b32 v253, s0, 47
	s_nop 1
	v_writelane_b32 v253, s1, 48
	s_lshl_b32 s0, s84, 6
	s_cmpk_lt_i32 s2, 0x300
	v_writelane_b32 v253, s0, 49
	s_cselect_b64 s[0:1], -1, 0
	s_add_u32 s95, s4, 0xa800800
	s_addc_u32 s8, s5, 0
	s_add_u32 s9, s4, 0xa801000
	v_writelane_b32 v253, s0, 50
	s_addc_u32 s10, s5, 0
	s_nop 0
	v_writelane_b32 v253, s1, 51
	s_add_u32 s0, s4, 0x1a800000
	s_addc_u32 s1, s5, 0
	v_writelane_b32 v253, s0, 52
	s_cmpk_lt_i32 s74, 0x100
	s_nop 0
	v_writelane_b32 v253, s1, 53
	s_cselect_b64 s[0:1], -1, 0
	v_writelane_b32 v253, s0, 54
	s_nop 1
	v_writelane_b32 v253, s1, 55
	s_add_u32 s0, s4, 0x18800000
	v_writelane_b32 v253, s4, 56
	s_addc_u32 s1, s5, 0
	s_cmpk_lt_i32 s2, 0x200
	v_writelane_b32 v253, s5, 57
	v_writelane_b32 v253, s0, 58
	s_movk_i32 s4, 0x61
	s_nop 0
	v_writelane_b32 v253, s1, 59
	s_cselect_b64 s[0:1], -1, 0
	v_writelane_b32 v253, s0, 60
	s_nop 1
	v_writelane_b32 v253, s1, 61
	s_lshl_b32 s0, s14, 6
	s_cmp_lt_i32 s14, 0
	s_mul_i32 s1, s14, 0x41
	s_cselect_b32 s0, s1, s0
	s_cselect_b32 s1, 49, 48
	s_mul_i32 s1, s14, s1
	s_cselect_b32 s4, s4, 0x60
	s_add_i32 s1, s1, s13
	s_mul_hi_i32 s5, s1, 0x2aaaaaab
	s_lshr_b32 s6, s5, 31
	s_ashr_i32 s5, s5, 2
	s_add_i32 s5, s5, s6
	s_mul_i32 s6, s5, 24
	s_sub_i32 s1, s1, s6
	s_bfe_i32 s6, s1, 0x80000
	s_bfe_u32 s6, s6, 0x3000c
	s_add_i32 s6, s1, s6
	s_mul_i32 s4, s14, s4
	s_and_b32 s7, s6, 0xf8
	s_add_i32 s4, s4, s13
	s_sub_i32 s1, s1, s7
	s_mul_hi_i32 s7, s4, 0x2aaaaaab
	s_lshr_b32 s11, s7, 31
	s_ashr_i32 s7, s7, 3
	s_add_i32 s7, s7, s11
	s_mul_i32 s11, s7, 48
	s_sub_i32 s4, s4, s11
	s_bfe_i32 s11, s4, 0x80000
	s_bfe_u32 s11, s11, 0x3000c
	s_add_i32 s11, s4, s11
	s_and_b32 s12, s11, 0xf8
	s_sub_i32 s4, s4, s12
	s_lshl_b32 s7, s7, 3
	s_sext_i32_i8 s4, s4
	s_add_i32 s0, s0, s13
	s_add_i32 s15, s7, s4
	s_ashr_i32 s4, s0, 31
	s_lshr_b32 s4, s4, 27
	s_add_i32 s4, s0, s4
	s_and_b32 s7, s4, 0xffe0
	s_sub_i32 s0, s0, s7
	s_bfe_i32 s7, s0, 0x80000
	s_bfe_u32 s7, s7, 0x3000c
	s_add_i32 s7, s0, s7
	s_and_b32 s12, s7, 0xf8
	s_sub_i32 s12, s0, s12
	s_lshl_b32 s0, s5, 3
	s_sext_i32_i8 s1, s1
	s_bfe_i32 s5, s6, 0x80000
	s_add_i32 s6, s0, s1
	s_bfe_i32 s0, s11, 0x80000
	s_sext_i32_i16 s0, s0
	v_writelane_b32 v253, s13, 62
	s_ashr_i32 s1, s0, 3
	s_lshr_b32 s0, s0, 3
	v_writelane_b32 v253, s1, 63
	s_bfe_i64 s[0:1], s[0:1], 0x100000
	v_writelane_b32 v254, s0, 0
	s_sext_i32_i16 s5, s5
	s_movk_i32 s11, 0xc00
	v_writelane_b32 v254, s1, 1
	s_ashr_i32 s0, s4, 5
	s_bfe_i32 s1, s7, 0x80000
	s_lshl_b32 s0, s0, 3
	s_sext_i32_i16 s4, s1
	s_sext_i32_i8 s1, s12
	s_add_i32 s12, s0, s1
	s_ashr_i32 s0, s5, 3
	v_writelane_b32 v254, s0, 2
	s_lshr_b32 s0, s5, 3
	s_bfe_i64 s[0:1], s[0:1], 0x100000
	s_lshl_b64 s[0:1], s[0:1], 19
	v_writelane_b32 v254, s0, 3
	s_ashr_i32 s7, s6, 31
	s_nop 0
	v_writelane_b32 v254, s1, 4
	v_writelane_b32 v254, s15, 5
	s_ashr_i32 s0, s15, 31
	v_writelane_b32 v254, s0, 6
	s_ashr_i32 s0, s4, 3
	v_writelane_b32 v254, s0, 7
	s_lshr_b32 s0, s4, 3
	s_mov_b32 s4, s6
	v_writelane_b32 v254, s4, 8
	s_nop 1
	v_writelane_b32 v254, s5, 9
	s_lshl_b64 s[4:5], s[6:7], 19
	s_add_u32 s4, s68, s4
	s_addc_u32 s5, s69, s5
	s_add_u32 s6, s4, 0x40000
	v_writelane_b32 v254, s4, 10
	s_addc_u32 s7, s5, 0
	s_abs_i32 s1, s84
	v_cvt_f32_u32_e32 v0, s1
	v_writelane_b32 v254, s5, 11
	v_writelane_b32 v254, s6, 12
	s_sub_i32 s4, 0, s1
	v_rcp_iflag_f32_e32 v0, v0
	v_writelane_b32 v254, s7, 13
	s_ashr_i32 s13, s12, 31
	v_writelane_b32 v254, s12, 14
	v_mul_f32_e32 v0, 0x4f7ffffe, v0
	v_cvt_u32_f32_e32 v0, v0
	v_writelane_b32 v254, s13, 15
	s_bfe_i64 s[6:7], s[0:1], 0x100000
	v_writelane_b32 v254, s6, 16
	v_readfirstlane_b32 s5, v0
	s_mul_i32 s4, s4, s5
	s_mul_hi_u32 s4, s5, s4
	s_add_i32 s5, s5, s4
	s_lshr_b32 s0, s5, 21
	v_writelane_b32 v254, s7, 17
	s_mul_i32 s4, s0, s1
	s_sub_i32 s4, 0x800, s4
	v_writelane_b32 v254, s14, 18
	s_lshr_b32 s5, s14, 31
	v_writelane_b32 v254, s5, 19
	s_add_i32 s5, s0, 1
	s_sub_i32 s6, s4, s1
	s_cmp_ge_u32 s4, s1
	s_cselect_b32 s0, s5, s0
	s_cselect_b32 s4, s6, s4
	s_add_i32 s5, s0, 1
	s_cmp_ge_u32 s4, s1
	s_cselect_b32 s0, s5, s0
	s_xor_b32 s0, s0, s33
	s_sub_i32 s37, s0, s33
	s_mul_i32 s1, s85, s84
	s_cmp_gt_i32 s37, 0
	s_mul_i32 s85, s1, s71
	s_cselect_b64 s[0:1], -1, 0
	v_writelane_b32 v254, s0, 20
	v_mov_b64_e32 v[0:1], 0x800
	s_movk_i32 s12, 0x140
	v_writelane_b32 v254, s1, 21
	s_add_i32 s0, s37, -1
	s_mul_i32 s1, s0, s33
	s_mul_hi_u32 s4, s0, s84
	s_add_i32 s4, s4, s1
	s_mul_i32 s0, s0, s84
	s_add_u32 s0, s0, s2
	s_addc_u32 s1, s4, s3
	s_ashr_i32 s4, s0, 31
	s_lshr_b32 s4, s4, 29
	s_add_i32 s4, s0, s4
	s_ashr_i32 s5, s4, 3
	s_and_b32 s4, s4, -8
	s_sub_i32 s4, s0, s4
	s_cmp_gt_i32 s4, -1
	v_writelane_b32 v254, s5, 22
	s_cselect_b64 s[6:7], -1, 0
	v_writelane_b32 v254, s6, 23
	s_lshl_b32 s5, s72, 3
	v_cmp_lt_i64_e64 s[0:1], s[0:1], v[0:1]
	v_writelane_b32 v254, s7, 24
	s_lshl_b32 s6, s74, 6
	v_writelane_b32 v254, s74, 25
	s_add_i32 s5, s6, s5
	v_writelane_b32 v254, s5, 26
	v_writelane_b32 v254, s0, 27
	s_mov_b64 s[74:75], s[16:17]
	s_mov_b64 s[72:73], s[18:19]
	v_writelane_b32 v254, s1, 28
	s_lshl_b32 s0, s4, 8
	v_writelane_b32 v254, s0, 29
	s_mul_i32 s0, s4, 0x101
	v_writelane_b32 v254, s0, 30
	s_add_i32 s0, s37, -2
	v_writelane_b32 v254, s0, 31
	s_lshl_b32 s0, s84, 11
	v_writelane_b32 v254, s0, 32
	s_add_i32 s0, 0, 0x20020
	v_writelane_b32 v254, s0, 33
	s_add_i32 s0, 0, 0x20024
	v_writelane_b32 v254, s0, 34
	s_add_i32 s0, 0, 0x22100
	v_writelane_b32 v254, s0, 35
	s_add_i32 s0, 0, 0x22900
	v_writelane_b32 v254, s0, 36
	v_writelane_b32 v254, s96, 37
	s_mov_b32 s14, 0xffff
	s_mov_b32 s5, 0
	v_writelane_b32 v254, s97, 38
	v_writelane_b32 v254, s76, 39
	s_nop 1
	v_writelane_b32 v254, s77, 40
	v_writelane_b32 v254, s78, 41
	s_nop 1
	v_writelane_b32 v254, s79, 42
	v_writelane_b32 v254, s80, 43
	s_nop 1
	v_writelane_b32 v254, s81, 44
	v_writelane_b32 v254, s74, 45
	s_nop 1
	v_writelane_b32 v254, s75, 46
	v_writelane_b32 v254, s72, 47
	s_nop 1
	v_writelane_b32 v254, s73, 48
	v_writelane_b32 v254, s62, 49
	s_nop 1
	v_writelane_b32 v254, s63, 50
	v_writelane_b32 v254, s64, 51
	s_nop 1
	v_writelane_b32 v254, s65, 52
	s_branch .LBB0_166

; __device__ __forceinline__ float bf2f(unsigned short v) { return __uint_as_float(((unsigned)v) << 16); }
; template <int DQK, bool MOBA>
; __device__ __forceinline__ void attn_unit(const Args& A, int b, int h, int qb, lptr lds) {
;     ...
;     int tid_o = threadIdx.x; asm volatile("" : "+v"(tid_o));
;     const int tid = tid_o, lane = tid & 63, r32 = lane & 31, hi = lane >> 5;
;     const int wid = __builtin_amdgcn_readfirstlane(tid >> 6);
;     const int tb = b * SEQ, q0 = qb * 256, own = qb, bh = b * NH + h;
;     const int qrow = tb + q0 + wid * 32 + r32;
;     const int qrel = wid * 32 + r32;
;     __syncthreads();
;     bf16x8 qf[NS];
;     {
;         const bf16* qp = A.Q + (size_t)qrow * A.q_pitch + h * DQK + 8 * hi;
; #pragma unroll
;         for (int s = 0; s < NS; ++s) qf[s] = *(const bf16x8*)(qp + 16 * s);
;     }
;     {
;         float ssn = 0.f;
; #pragma unroll
;         for (int s = 0; s < 8; ++s)
; #pragma unroll
;             for (int e = 0; e < 8; ++e) { const float f = bf2f((unsigned short)qf[s][e]); ssn += f * f; }
;         ssn += __shfl_xor(ssn, 32);
;         const float scn = __builtin_amdgcn_rsqf(ssn * (1.0f / 128.0f) + 1e-6f) * A.qscale;
.LBB0_761:
	s_lshl_b32 s0, s53, 2
	s_add_i32 s0, s0, s50
	s_ashr_i32 s1, s0, 31
	s_lshr_b32 s4, s1, 29
	s_add_i32 s4, s0, s4
	s_and_b32 s5, s4, -8
	v_mov_b32_e32 v162, v202
	s_sub_i32 s19, s0, s5
	s_lshl_b32 s4, s4, 8
	v_readfirstlane_b32 s5, v162
	s_and_b32 s70, s4, 0xfffff800
	s_lshl_b32 s17, s18, 8
	s_ashr_i32 s71, s5, 1
	s_add_i32 s42, s17, s70
	s_andn2_b32 s71, s71, 31
	v_and_b32_e32 v83, 31, v162
	s_add_i32 s4, s71, s42
	v_or_b32_e32 v160, s4, v83
	v_mov_b64_e32 v[0:1], s[88:89]
	s_movk_i32 s4, 0x1800
	s_lshl_b32 s46, s19, 7
	v_and_b32_e32 v3, 64, v206
	v_bfe_u32 v82, v162, 5, 1
	v_mad_i64_i32 v[0:1], s[4:5], v160, s4, v[0:1]
	s_ashr_i32 s47, s46, 31
	v_xor_b32_e32 v2, 32, v206
	v_add_u32_e32 v89, 64, v3
	v_lshl_add_u64 v[0:1], s[46:47], 1, v[0:1]
	v_lshlrev_b32_e32 v36, 4, v82
	v_mov_b32_e32 v37, v181
	v_cmp_lt_i32_e32 vcc, v2, v89
	v_lshl_add_u64 v[0:1], v[0:1], 0, v[36:37]
	v_and_b32_e32 v37, 32, v162
	v_cndmask_b32_e32 v2, v206, v2, vcc
	s_barrier
	v_mov_b32_e32 v230, 0x14a00
	v_mov_b32_e32 v229, 0x40000000
	ds_write_b32 v230, v209
	global_load_dwordx4 v[44:47], v[0:1], off offset:224
	global_load_dwordx4 v[52:55], v[0:1], off offset:192
	global_load_dwordx4 v[60:63], v[0:1], off offset:160
	global_load_dwordx4 v[68:71], v[0:1], off offset:128
	global_load_dwordx4 v[76:79], v[0:1], off offset:96
	global_load_dwordx4 v[84:87], v[0:1], off offset:64
	v_lshlrev_b32_e32 v170, 2, v2
	global_load_dwordx4 v[28:31], v37, s[30:31] offset:16
	global_load_dwordx4 v[32:35], v37, s[30:31]
	global_load_dwordx4 v[90:93], v[0:1], off
	global_load_dwordx4 v[94:97], v[0:1], off offset:32
	global_load_dwordx4 v[20:23], v37, s[30:31] offset:80
	global_load_dwordx4 v[24:27], v37, s[30:31] offset:64
	global_load_dwordx4 v[12:15], v37, s[30:31] offset:144
	global_load_dwordx4 v[16:19], v37, s[30:31] offset:128
	global_load_dwordx4 v[4:7], v37, s[30:31] offset:208
	global_load_dwordx4 v[8:11], v37, s[30:31] offset:192
	global_load_dwordx4 v[0:3], v37, s[30:31] offset:256
	s_lshl_b64 s[0:1], s[0:1], 12
	s_add_u32 s0, s66, s0
	v_ashrrev_i32_e32 v163, 31, v162
	s_addc_u32 s1, s67, s1
	v_ashrrev_i32_e32 v161, 31, v160
	s_cmp_gt_u32 s18, 3
	s_waitcnt vmcnt(8)
	v_and_b32_e32 v175, 0xffff0000, v90
	v_lshlrev_b32_e32 v174, 16, v90
	v_and_b32_e32 v169, 0xffff0000, v91
	v_lshlrev_b32_e32 v168, 16, v91
	v_pk_mul_f32 v[90:91], v[174:175], v[174:175]
	v_pk_mul_f32 v[172:173], v[168:169], v[168:169]
	v_add_f32_e32 v88, v90, v91
	v_and_b32_e32 v167, 0xffff0000, v92
	v_lshlrev_b32_e32 v166, 16, v92
	v_add_f32_e32 v88, v172, v88
	v_and_b32_e32 v165, 0xffff0000, v93
	v_lshlrev_b32_e32 v164, 16, v93
	v_pk_mul_f32 v[92:93], v[166:167], v[166:167]
	v_add_f32_e32 v88, v173, v88
	v_add_f32_e32 v88, v92, v88
	v_pk_mul_f32 v[148:149], v[164:165], v[164:165]
	v_add_f32_e32 v88, v93, v88
	s_waitcnt vmcnt(7)
	v_and_b32_e32 v159, 0xffff0000, v94
	v_lshlrev_b32_e32 v158, 16, v94
	v_add_f32_e32 v88, v148, v88
	v_and_b32_e32 v157, 0xffff0000, v95
	v_lshlrev_b32_e32 v156, 16, v95
	v_pk_mul_f32 v[94:95], v[158:159], v[158:159]
	v_add_f32_e32 v88, v149, v88
	v_add_f32_e32 v88, v94, v88
	v_pk_mul_f32 v[146:147], v[156:157], v[156:157]
	v_add_f32_e32 v88, v95, v88
	v_and_b32_e32 v155, 0xffff0000, v96
	v_lshlrev_b32_e32 v154, 16, v96
	v_add_f32_e32 v88, v146, v88
	v_and_b32_e32 v153, 0xffff0000, v97
	v_lshlrev_b32_e32 v152, 16, v97
	v_pk_mul_f32 v[96:97], v[154:155], v[154:155]
	v_add_f32_e32 v88, v147, v88
	v_add_f32_e32 v88, v96, v88
	v_pk_mul_f32 v[144:145], v[152:153], v[152:153]
	v_add_f32_e32 v88, v97, v88
	v_and_b32_e32 v151, 0xffff0000, v84
	v_lshlrev_b32_e32 v150, 16, v84
	v_add_f32_e32 v88, v144, v88
	v_and_b32_e32 v141, 0xffff0000, v85
	v_lshlrev_b32_e32 v140, 16, v85
	v_pk_mul_f32 v[84:85], v[150:151], v[150:151]
	v_add_f32_e32 v88, v145, v88
	v_add_f32_e32 v84, v84, v88
	v_pk_mul_f32 v[142:143], v[140:141], v[140:141]
	v_add_f32_e32 v84, v85, v84
	v_and_b32_e32 v81, 0xffff0000, v86
	v_lshlrev_b32_e32 v80, 16, v86
	v_add_f32_e32 v84, v142, v84
	v_and_b32_e32 v39, 0xffff0000, v47
	v_lshlrev_b32_e32 v38, 16, v47
	v_and_b32_e32 v41, 0xffff0000, v46
	v_lshlrev_b32_e32 v40, 16, v46
	v_and_b32_e32 v47, 0xffff0000, v55
	v_lshlrev_b32_e32 v46, 16, v55
	v_and_b32_e32 v49, 0xffff0000, v54
	v_lshlrev_b32_e32 v48, 16, v54
	v_and_b32_e32 v55, 0xffff0000, v63
	v_lshlrev_b32_e32 v54, 16, v63
	v_and_b32_e32 v57, 0xffff0000, v62
	v_lshlrev_b32_e32 v56, 16, v62
	v_and_b32_e32 v63, 0xffff0000, v71
	v_lshlrev_b32_e32 v62, 16, v71
	v_and_b32_e32 v65, 0xffff0000, v70
	v_lshlrev_b32_e32 v64, 16, v70
	v_and_b32_e32 v71, 0xffff0000, v79
	v_lshlrev_b32_e32 v70, 16, v79
	v_and_b32_e32 v73, 0xffff0000, v78
	v_lshlrev_b32_e32 v72, 16, v78
	v_and_b32_e32 v79, 0xffff0000, v87
	v_lshlrev_b32_e32 v78, 16, v87
	v_pk_mul_f32 v[86:87], v[80:81], v[80:81]
	v_add_f32_e32 v84, v143, v84
	v_add_f32_e32 v84, v86, v84
	v_pk_mul_f32 v[138:139], v[78:79], v[78:79]
	v_add_f32_e32 v84, v87, v84
	v_and_b32_e32 v75, 0xffff0000, v77
	v_lshlrev_b32_e32 v74, 16, v77
	v_and_b32_e32 v77, 0xffff0000, v76
	v_lshlrev_b32_e32 v76, 16, v76
	v_add_f32_e32 v84, v138, v84
	v_pk_mul_f32 v[136:137], v[76:77], v[76:77]
	v_add_f32_e32 v84, v139, v84
	v_add_f32_e32 v84, v136, v84
	v_pk_mul_f32 v[134:135], v[74:75], v[74:75]
	v_add_f32_e32 v84, v137, v84
	v_add_f32_e32 v84, v134, v84
	v_pk_mul_f32 v[132:133], v[72:73], v[72:73]
	v_add_f32_e32 v84, v135, v84
	v_add_f32_e32 v84, v132, v84
	v_pk_mul_f32 v[130:131], v[70:71], v[70:71]
	v_add_f32_e32 v84, v133, v84
	v_and_b32_e32 v67, 0xffff0000, v69
	v_lshlrev_b32_e32 v66, 16, v69
	v_and_b32_e32 v69, 0xffff0000, v68
	v_lshlrev_b32_e32 v68, 16, v68
	v_add_f32_e32 v84, v130, v84
; __device__ __forceinline__ unsigned cvt_pk_bf16(float lo, float hi) { f32x2 v = {lo, hi}; bf16x2_t b = __builtin_convertvector(v, bf16x2_t); return __builtin_bit_cast(unsigned, b); }
; __device__ __forceinline__ float bf2f(unsigned short v) { return __uint_as_float(((unsigned)v) << 16); }
; template <int DQK, bool MOBA>
; __device__ __forceinline__ void attn_unit(const Args& A, int b, int h, int qb, lptr lds) {
;     ...
;         ssn += __shfl_xor(ssn, 32);
;         const float scn = __builtin_amdgcn_rsqf(ssn * (1.0f / 128.0f) + 1e-6f) * A.qscale;
; #pragma unroll
;         for (int s = 0; s < 8; ++s) {
;             const f32x4 g0 = *(const f32x4*)(A.gq_n + 16 * s + 8 * hi), g1 = *(const f32x4*)(A.gq_n + 16 * s + 8 * hi + 4);
;             u32x4 w;
;             w.x = cvt_pk_bf16(bf2f((unsigned short)qf[s][0]) * scn * g0[0], bf2f((unsigned short)qf[s][1]) * scn * g0[1]);
;             w.y = cvt_pk_bf16(bf2f((unsigned short)qf[s][2]) * scn * g0[2], bf2f((unsigned short)qf[s][3]) * scn * g0[3]);
;             w.z = cvt_pk_bf16(bf2f((unsigned short)qf[s][4]) * scn * g1[0], bf2f((unsigned short)qf[s][5]) * scn * g1[1]);
;             w.w = cvt_pk_bf16(bf2f((unsigned short)qf[s][6]) * scn * g1[2], bf2f((unsigned short)qf[s][7]) * scn * g1[3]);
;             qf[s] = __builtin_bit_cast(bf16x8, w);
;         }
;     ...
;         lut[tid] = A.lut[h * 1024 + tid]; lut[tid + 512] = A.lut[h * 1024 + tid + 512];
;         km[tid] = A.kmean[(size_t)bh * 1024 + tid]; km[tid + 512] = A.kmean[(size_t)bh * 1024 + tid + 512];
;         pq = A.pos[qrow];
	v_pk_mul_f32 v[128:129], v[68:69], v[68:69]
	v_add_f32_e32 v84, v131, v84
	v_add_f32_e32 v84, v128, v84
	v_pk_mul_f32 v[126:127], v[66:67], v[66:67]
	v_add_f32_e32 v84, v129, v84
	v_add_f32_e32 v84, v126, v84
	v_pk_mul_f32 v[124:125], v[64:65], v[64:65]
	v_add_f32_e32 v84, v127, v84
	v_add_f32_e32 v84, v124, v84
	v_pk_mul_f32 v[122:123], v[62:63], v[62:63]
	v_add_f32_e32 v84, v125, v84
	v_and_b32_e32 v59, 0xffff0000, v61
	v_lshlrev_b32_e32 v58, 16, v61
	v_and_b32_e32 v61, 0xffff0000, v60
	v_lshlrev_b32_e32 v60, 16, v60
	v_add_f32_e32 v84, v122, v84
	v_pk_mul_f32 v[120:121], v[60:61], v[60:61]
	v_add_f32_e32 v84, v123, v84
	v_add_f32_e32 v84, v120, v84
	v_pk_mul_f32 v[118:119], v[58:59], v[58:59]
	v_add_f32_e32 v84, v121, v84
	v_add_f32_e32 v84, v118, v84
	v_pk_mul_f32 v[116:117], v[56:57], v[56:57]
	v_add_f32_e32 v84, v119, v84
	v_add_f32_e32 v84, v116, v84
	v_pk_mul_f32 v[114:115], v[54:55], v[54:55]
	v_add_f32_e32 v84, v117, v84
	v_and_b32_e32 v51, 0xffff0000, v53
	v_lshlrev_b32_e32 v50, 16, v53
	v_and_b32_e32 v53, 0xffff0000, v52
	v_lshlrev_b32_e32 v52, 16, v52
	v_add_f32_e32 v84, v114, v84
	v_pk_mul_f32 v[112:113], v[52:53], v[52:53]
	v_add_f32_e32 v84, v115, v84
	v_add_f32_e32 v84, v112, v84
	v_pk_mul_f32 v[110:111], v[50:51], v[50:51]
	v_add_f32_e32 v84, v113, v84
	v_add_f32_e32 v84, v110, v84
	v_pk_mul_f32 v[108:109], v[48:49], v[48:49]
	v_add_f32_e32 v84, v111, v84
	v_add_f32_e32 v84, v108, v84
	v_pk_mul_f32 v[106:107], v[46:47], v[46:47]
	v_add_f32_e32 v84, v109, v84
	v_and_b32_e32 v43, 0xffff0000, v45
	v_lshlrev_b32_e32 v42, 16, v45
	v_and_b32_e32 v45, 0xffff0000, v44
	v_lshlrev_b32_e32 v44, 16, v44
	v_add_f32_e32 v84, v106, v84
	v_pk_mul_f32 v[104:105], v[44:45], v[44:45]
	v_add_f32_e32 v84, v107, v84
	v_add_f32_e32 v84, v104, v84
	v_pk_mul_f32 v[102:103], v[42:43], v[42:43]
	v_add_f32_e32 v84, v105, v84
	v_add_f32_e32 v84, v102, v84
	v_pk_mul_f32 v[100:101], v[40:41], v[40:41]
	v_add_f32_e32 v84, v103, v84
	v_add_f32_e32 v84, v100, v84
	v_pk_mul_f32 v[98:99], v[38:39], v[38:39]
	v_add_f32_e32 v84, v101, v84
	v_add_f32_e32 v84, v98, v84
	v_add_f32_e32 v84, v99, v84
	ds_bpermute_b32 v85, v170, v84
	global_load_dwordx4 v[90:93], v37, s[30:31] offset:272
	global_load_dwordx4 v[94:97], v37, s[30:31] offset:336
	global_load_dwordx4 v[98:101], v37, s[30:31] offset:320
	global_load_dwordx4 v[102:105], v37, s[30:31] offset:400
	global_load_dwordx4 v[106:109], v37, s[30:31] offset:384
	global_load_dwordx4 v[142:145], v37, s[30:31] offset:464
	global_load_dwordx4 v[146:149], v37, s[30:31] offset:448
	s_waitcnt lgkmcnt(0)
	v_add_f32_e32 v84, v84, v85
	v_fmamk_f32 v84, v84, 0x3c000000, v204
	v_rsq_f32_e32 v84, v84
	s_nop 0
	v_mul_f32_e32 v88, 0x3e0293ee, v84
	v_pk_mul_f32 v[84:85], v[88:89], v[174:175] op_sel_hi:[0,1]
	v_pk_mul_f32 v[32:33], v[32:33], v[84:85]
	s_nop 0
	v_cvt_pk_bf16_f32 v112, v32, v33
	v_pk_mul_f32 v[32:33], v[88:89], v[168:169] op_sel_hi:[0,1]
	v_pk_mul_f32 v[32:33], v[34:35], v[32:33]
	s_nop 0
	v_cvt_pk_bf16_f32 v113, v32, v33
	v_pk_mul_f32 v[32:33], v[88:89], v[166:167] op_sel_hi:[0,1]
	v_pk_mul_f32 v[28:29], v[28:29], v[32:33]
	s_nop 0
	v_cvt_pk_bf16_f32 v114, v28, v29
	v_pk_mul_f32 v[28:29], v[88:89], v[164:165] op_sel_hi:[0,1]
	v_pk_mul_f32 v[28:29], v[30:31], v[28:29]
	s_nop 0
	v_cvt_pk_bf16_f32 v37, v28, v29
	v_pk_mul_f32 v[28:29], v[88:89], v[158:159] op_sel_hi:[0,1]
	s_waitcnt vmcnt(12)
	v_pk_mul_f32 v[24:25], v[24:25], v[28:29]
	v_lshrrev_b32_e32 v30, 16, v37
	v_cvt_pk_bf16_f32 v116, v24, v25
	v_pk_mul_f32 v[24:25], v[88:89], v[156:157] op_sel_hi:[0,1]
	v_pk_mul_f32 v[24:25], v[26:27], v[24:25]
	v_and_b32_e32 v29, 0xffff0000, v116
	v_cvt_pk_bf16_f32 v117, v24, v25
	v_pk_mul_f32 v[24:25], v[88:89], v[154:155] op_sel_hi:[0,1]
	v_pk_mul_f32 v[20:21], v[20:21], v[24:25]
	v_lshlrev_b32_e32 v28, 16, v116
	v_cvt_pk_bf16_f32 v118, v20, v21
	v_pk_mul_f32 v[20:21], v[88:89], v[152:153] op_sel_hi:[0,1]
	v_pk_mul_f32 v[20:21], v[22:23], v[20:21]
	v_and_b32_e32 v27, 0xffff0000, v118
	v_cvt_pk_bf16_f32 v84, v20, v21
	v_pk_mul_f32 v[20:21], v[88:89], v[150:151] op_sel_hi:[0,1]
	s_waitcnt vmcnt(10)
	v_pk_mul_f32 v[16:17], v[16:17], v[20:21]
	v_lshl_add_u64 v[20:21], v[162:163], 2, s[0:1]
	v_cvt_pk_bf16_f32 v120, v16, v17
	v_pk_mul_f32 v[16:17], v[88:89], v[140:141] op_sel_hi:[0,1]
	v_pk_mul_f32 v[16:17], v[18:19], v[16:17]
	v_lshl_add_u32 v18, s19, 10, v162
	v_cvt_pk_bf16_f32 v121, v16, v17
	v_pk_mul_f32 v[16:17], v[88:89], v[80:81] op_sel_hi:[0,1]
	v_pk_mul_f32 v[12:13], v[12:13], v[16:17]
	v_ashrrev_i32_e32 v19, 31, v18
	v_cvt_pk_bf16_f32 v122, v12, v13
	v_pk_mul_f32 v[12:13], v[88:89], v[78:79] op_sel_hi:[0,1]
	v_pk_mul_f32 v[12:13], v[14:15], v[12:13]
	v_lshl_add_u64 v[18:19], v[18:19], 2, s[62:63]
	v_cvt_pk_bf16_f32 v80, v12, v13
	v_pk_mul_f32 v[12:13], v[88:89], v[76:77] op_sel_hi:[0,1]
	s_waitcnt vmcnt(8)
	v_pk_mul_f32 v[8:9], v[8:9], v[12:13]
	global_load_dword v23, v[18:19], off
	s_nop 0
	global_load_dword v18, v[18:19], off offset:2048
	s_nop 0
	global_load_dword v19, v[20:21], off
	s_nop 0
	global_load_dword v20, v[20:21], off offset:2048
	v_cvt_pk_bf16_f32 v124, v8, v9
	v_pk_mul_f32 v[8:9], v[88:89], v[74:75] op_sel_hi:[0,1]
	v_pk_mul_f32 v[8:9], v[10:11], v[8:9]
	v_lshrrev_b32_e32 v22, 16, v84
	v_cvt_pk_bf16_f32 v125, v8, v9
	v_pk_mul_f32 v[8:9], v[88:89], v[72:73] op_sel_hi:[0,1]
	v_pk_mul_f32 v[4:5], v[4:5], v[8:9]
	v_lshrrev_b32_e32 v16, 16, v80
	v_cvt_pk_bf16_f32 v126, v4, v5
	v_pk_mul_f32 v[4:5], v[88:89], v[70:71] op_sel_hi:[0,1]
	v_pk_mul_f32 v[4:5], v[6:7], v[4:5]
	s_mov_b64 s[0:1], -1
	v_cvt_pk_bf16_f32 v81, v4, v5
	v_pk_mul_f32 v[4:5], v[88:89], v[68:69] op_sel_hi:[0,1]
	s_waitcnt vmcnt(11)
; __device__ __forceinline__ unsigned cvt_pk_bf16(float lo, float hi) { f32x2 v = {lo, hi}; bf16x2_t b = __builtin_convertvector(v, bf16x2_t); return __builtin_bit_cast(unsigned, b); }
; __device__ __forceinline__ float bf2f(unsigned short v) { return __uint_as_float(((unsigned)v) << 16); }
; template <int DQK, bool MOBA>
; __device__ __forceinline__ void attn_unit(const Args& A, int b, int h, int qb, lptr lds) {
;     ...
;             w.x = cvt_pk_bf16(bf2f((unsigned short)qf[s][0]) * scn * g0[0], bf2f((unsigned short)qf[s][1]) * scn * g0[1]);
;             w.y = cvt_pk_bf16(bf2f((unsigned short)qf[s][2]) * scn * g0[2], bf2f((unsigned short)qf[s][3]) * scn * g0[3]);
;             w.z = cvt_pk_bf16(bf2f((unsigned short)qf[s][4]) * scn * g1[0], bf2f((unsigned short)qf[s][5]) * scn * g1[1]);
;             w.w = cvt_pk_bf16(bf2f((unsigned short)qf[s][6]) * scn * g1[2], bf2f((unsigned short)qf[s][7]) * scn * g1[3]);
;             qf[s] = __builtin_bit_cast(bf16x8, w);
;         }
;     ...
;         lut[tid] = A.lut[h * 1024 + tid]; lut[tid + 512] = A.lut[h * 1024 + tid + 512];
;         km[tid] = A.kmean[(size_t)bh * 1024 + tid]; km[tid + 512] = A.kmean[(size_t)bh * 1024 + tid + 512];
;         pq = A.pos[qrow];
;         __syncthreads();
	v_pk_mul_f32 v[0:1], v[0:1], v[4:5]
	v_lshrrev_b32_e32 v6, 16, v81
	v_cvt_pk_bf16_f32 v128, v0, v1
	v_pk_mul_f32 v[0:1], v[88:89], v[66:67] op_sel_hi:[0,1]
	v_pk_mul_f32 v[0:1], v[2:3], v[0:1]
	v_lshl_add_u64 v[2:3], v[160:161], 2, s[54:55]
	global_load_dword v171, v[2:3], off
	v_cvt_pk_bf16_f32 v129, v0, v1
	v_pk_mul_f32 v[0:1], v[88:89], v[64:65] op_sel_hi:[0,1]
	s_waitcnt vmcnt(11)
	v_pk_mul_f32 v[0:1], v[90:91], v[0:1]
	v_lshlrev_b32_e32 v15, 16, v37
	v_cvt_pk_bf16_f32 v130, v0, v1
	v_pk_mul_f32 v[0:1], v[88:89], v[62:63] op_sel_hi:[0,1]
	v_pk_mul_f32 v[0:1], v[92:93], v[0:1]
	v_lshlrev_b32_e32 v14, 16, v30
	v_cvt_pk_bf16_f32 v85, v0, v1
	v_pk_mul_f32 v[0:1], v[88:89], v[60:61] op_sel_hi:[0,1]
	s_waitcnt vmcnt(9)
	v_pk_mul_f32 v[0:1], v[98:99], v[0:1]
	v_lshrrev_b32_e32 v4, 16, v85
	v_cvt_pk_bf16_f32 v132, v0, v1
	v_pk_mul_f32 v[0:1], v[88:89], v[58:59] op_sel_hi:[0,1]
	v_pk_mul_f32 v[0:1], v[100:101], v[0:1]
	v_lshlrev_b32_e32 v13, 16, v84
	v_cvt_pk_bf16_f32 v133, v0, v1
	v_pk_mul_f32 v[0:1], v[88:89], v[56:57] op_sel_hi:[0,1]
	v_pk_mul_f32 v[0:1], v[94:95], v[0:1]
	v_lshlrev_b32_e32 v12, 16, v22
	v_cvt_pk_bf16_f32 v134, v0, v1
	v_pk_mul_f32 v[0:1], v[88:89], v[54:55] op_sel_hi:[0,1]
	v_pk_mul_f32 v[0:1], v[96:97], v[0:1]
	v_lshlrev_b32_e32 v11, 16, v80
	v_cvt_pk_bf16_f32 v86, v0, v1
	v_pk_mul_f32 v[0:1], v[88:89], v[52:53] op_sel_hi:[0,1]
	s_waitcnt vmcnt(7)
	v_pk_mul_f32 v[0:1], v[106:107], v[0:1]
	v_lshrrev_b32_e32 v17, 16, v86
	v_cvt_pk_bf16_f32 v136, v0, v1
	v_pk_mul_f32 v[0:1], v[88:89], v[50:51] op_sel_hi:[0,1]
	v_pk_mul_f32 v[0:1], v[108:109], v[0:1]
	v_lshlrev_b32_e32 v10, 16, v16
	v_cvt_pk_bf16_f32 v137, v0, v1
	v_pk_mul_f32 v[0:1], v[88:89], v[48:49] op_sel_hi:[0,1]
	v_pk_mul_f32 v[0:1], v[102:103], v[0:1]
	v_lshlrev_b32_e32 v9, 16, v81
	v_cvt_pk_bf16_f32 v138, v0, v1
	v_pk_mul_f32 v[0:1], v[88:89], v[46:47] op_sel_hi:[0,1]
	v_pk_mul_f32 v[0:1], v[104:105], v[0:1]
	v_lshlrev_b32_e32 v8, 16, v6
	v_cvt_pk_bf16_f32 v87, v0, v1
	v_pk_mul_f32 v[0:1], v[88:89], v[44:45] op_sel_hi:[0,1]
	s_waitcnt vmcnt(5)
	v_pk_mul_f32 v[0:1], v[146:147], v[0:1]
	v_lshrrev_b32_e32 v21, 16, v87
	v_cvt_pk_bf16_f32 v140, v0, v1
	v_pk_mul_f32 v[0:1], v[88:89], v[42:43] op_sel_hi:[0,1]
	v_pk_mul_f32 v[0:1], v[148:149], v[0:1]
	v_lshlrev_b32_e32 v7, 16, v85
	v_cvt_pk_bf16_f32 v141, v0, v1
	v_pk_mul_f32 v[0:1], v[88:89], v[40:41] op_sel_hi:[0,1]
	v_pk_mul_f32 v[0:1], v[142:143], v[0:1]
	v_lshlrev_b32_e32 v6, 16, v4
	v_cvt_pk_bf16_f32 v142, v0, v1
	v_pk_mul_f32 v[0:1], v[88:89], v[38:39] op_sel_hi:[0,1]
	v_pk_mul_f32 v[0:1], v[144:145], v[0:1]
	v_lshlrev_b32_e32 v5, 16, v86
	v_cvt_pk_bf16_f32 v88, v0, v1
	v_lshl_add_u32 v1, v162, 2, 0
	v_lshrrev_b32_e32 v0, 16, v88
	v_add_u32_e32 v2, 0x12a00, v1
	v_add_u32_e32 v1, 0x13a00, v1
	s_waitcnt vmcnt(3)
	ds_write2st64_b32 v2, v23, v18 offset1:8
	s_waitcnt vmcnt(1)
	ds_write2st64_b32 v1, v19, v20 offset1:8
	v_lshlrev_b32_e32 v4, 16, v17
	v_lshlrev_b32_e32 v3, 16, v87
	v_lshlrev_b32_e32 v2, 16, v21
	v_lshlrev_b32_e32 v1, 16, v88
	v_lshlrev_b32_e32 v0, 16, v0
	v_and_b32_e32 v17, 0xffff0000, v113
	v_lshlrev_b32_e32 v16, 16, v113
	v_and_b32_e32 v23, 0xffff0000, v112
	v_lshlrev_b32_e32 v22, 16, v112
	v_and_b32_e32 v21, 0xffff0000, v114
	v_lshlrev_b32_e32 v20, 16, v114
	v_and_b32_e32 v19, 0xffff0000, v117
	v_lshlrev_b32_e32 v18, 16, v117
	v_lshlrev_b32_e32 v26, 16, v118
	v_and_b32_e32 v25, 0xffff0000, v121
	v_lshlrev_b32_e32 v24, 16, v121
	v_and_b32_e32 v35, 0xffff0000, v120
	v_lshlrev_b32_e32 v34, 16, v120
	v_and_b32_e32 v33, 0xffff0000, v122
	v_lshlrev_b32_e32 v32, 16, v122
	v_and_b32_e32 v31, 0xffff0000, v125
	v_lshlrev_b32_e32 v30, 16, v125
	v_and_b32_e32 v43, 0xffff0000, v124
	v_lshlrev_b32_e32 v42, 16, v124
	v_and_b32_e32 v41, 0xffff0000, v126
	v_lshlrev_b32_e32 v40, 16, v126
	v_and_b32_e32 v39, 0xffff0000, v129
	v_lshlrev_b32_e32 v38, 16, v129
	v_and_b32_e32 v49, 0xffff0000, v128
	v_lshlrev_b32_e32 v48, 16, v128
	v_and_b32_e32 v47, 0xffff0000, v130
	v_lshlrev_b32_e32 v46, 16, v130
	v_and_b32_e32 v45, 0xffff0000, v133
	v_lshlrev_b32_e32 v44, 16, v133
	v_and_b32_e32 v55, 0xffff0000, v132
	v_lshlrev_b32_e32 v54, 16, v132
	v_and_b32_e32 v53, 0xffff0000, v134
	v_lshlrev_b32_e32 v52, 16, v134
	v_and_b32_e32 v51, 0xffff0000, v137
	v_lshlrev_b32_e32 v50, 16, v137
	v_and_b32_e32 v61, 0xffff0000, v136
	v_lshlrev_b32_e32 v60, 16, v136
	v_and_b32_e32 v59, 0xffff0000, v138
	v_lshlrev_b32_e32 v58, 16, v138
	v_and_b32_e32 v57, 0xffff0000, v141
	v_lshlrev_b32_e32 v56, 16, v141
	v_and_b32_e32 v65, 0xffff0000, v140
	v_lshlrev_b32_e32 v64, 16, v140
	v_and_b32_e32 v63, 0xffff0000, v142
	v_lshlrev_b32_e32 v62, 16, v142
	s_waitcnt lgkmcnt(0)
	s_barrier
	s_cbranch_scc0 .LBB0_769
; #define LAS __attribute__((address_space(3)))
; __device__ __forceinline__ float bf2f(unsigned short v) { return __uint_as_float(((unsigned)v) << 16); }
; template <int DQK, bool MOBA>
; __device__ __forceinline__ void attn_unit(const Args& A, int b, int h, int qb, lptr lds) {
;     ...
;             float g[7];
; #pragma unroll
;             for (int j = 0; j < 7; ++j) {
;                 float a = 0.f;
;                 if (j < own) {
; #pragma unroll
;                     for (int s = 0; s < NS; ++s) {
;                         const f32x4 k0 = *(const LAS f32x4*)(km + j * 128 + 16 * s + 8 * hi), k1 = *(const LAS f32x4*)(km + j * 128 + 16 * s + 8 * hi + 4);
;                         a += bf2f((unsigned short)qf[s][0]) * k0[0] + bf2f((unsigned short)qf[s][1]) * k0[1] + bf2f((unsigned short)qf[s][2]) * k0[2] + bf2f((unsigned short)qf[s][3]) * k0[3];
;                         a += bf2f((unsigned short)qf[s][4]) * k1[0] + bf2f((unsigned short)qf[s][5]) * k1[1] + bf2f((unsigned short)qf[s][6]) * k1[2] + bf2f((unsigned short)qf[s][7]) * k1[3];
;                     }
;                 }
;                 a += __shfl_xor(a, 32);
;                 g[j] = a;
;             }
	v_lshlrev_b32_e32 v66, 3, v82
	v_lshl_add_u32 v66, v66, 2, 0
	v_add_u32_e32 v66, 0x13a00, v66
	ds_read_b128 v[68:71], v66
	ds_read_b128 v[72:75], v66 offset:16
	s_cmp_lg_u32 s18, 4
	v_mov_b32_e32 v67, 0
	s_cselect_b64 s[4:5], -1, 0
	s_waitcnt lgkmcnt(1)
	v_mul_f32_e32 v69, v69, v23
	v_fmac_f32_e32 v69, v68, v22
	v_fmac_f32_e32 v69, v70, v16
	v_fmac_f32_e32 v69, v71, v17
	v_add_f32_e32 v68, 0, v69
	s_waitcnt lgkmcnt(0)
	v_mul_f32_e32 v69, v73, v21
	v_fmac_f32_e32 v69, v72, v20
	v_fmac_f32_e32 v69, v74, v15
	v_fmac_f32_e32 v69, v75, v14
	v_add_f32_e32 v72, v68, v69
	ds_read_b128 v[68:71], v66 offset:64
	s_cmp_eq_u32 s18, 4
	s_waitcnt lgkmcnt(0)
	v_mul_f32_e32 v69, v69, v29
	v_fmac_f32_e32 v69, v68, v28
	v_fmac_f32_e32 v69, v70, v18
	v_fmac_f32_e32 v69, v71, v19
	v_add_f32_e32 v72, v72, v69
	ds_read_b128 v[68:71], v66 offset:80
	s_waitcnt lgkmcnt(0)
	v_mul_f32_e32 v69, v69, v27
	v_fmac_f32_e32 v69, v68, v26
	v_fmac_f32_e32 v69, v70, v13
	v_fmac_f32_e32 v69, v71, v12
	v_add_f32_e32 v72, v72, v69
	ds_read_b128 v[68:71], v66 offset:128
	s_waitcnt lgkmcnt(0)
	v_mul_f32_e32 v69, v69, v35
	v_fmac_f32_e32 v69, v68, v34
	v_fmac_f32_e32 v69, v70, v24
	v_fmac_f32_e32 v69, v71, v25
	v_add_f32_e32 v72, v72, v69
	ds_read_b128 v[68:71], v66 offset:144
	s_waitcnt lgkmcnt(0)
	v_mul_f32_e32 v69, v69, v33
	v_fmac_f32_e32 v69, v68, v32
	v_fmac_f32_e32 v69, v70, v11
	v_fmac_f32_e32 v69, v71, v10
	v_add_f32_e32 v72, v72, v69
	ds_read_b128 v[68:71], v66 offset:192
	s_waitcnt lgkmcnt(0)
	v_mul_f32_e32 v69, v69, v43
	v_fmac_f32_e32 v69, v68, v42
	v_fmac_f32_e32 v69, v70, v30
	v_fmac_f32_e32 v69, v71, v31
	v_add_f32_e32 v72, v72, v69
	ds_read_b128 v[68:71], v66 offset:208
	s_waitcnt lgkmcnt(0)
	v_mul_f32_e32 v69, v69, v41
	v_fmac_f32_e32 v69, v68, v40
	v_fmac_f32_e32 v69, v70, v9
	v_fmac_f32_e32 v69, v71, v8
	v_add_f32_e32 v72, v72, v69
	ds_read_b128 v[68:71], v66 offset:256
	s_waitcnt lgkmcnt(0)
	v_mul_f32_e32 v69, v69, v49
	v_fmac_f32_e32 v69, v68, v48
	v_fmac_f32_e32 v69, v70, v38
	v_fmac_f32_e32 v69, v71, v39
	v_add_f32_e32 v72, v72, v69
	ds_read_b128 v[68:71], v66 offset:272
	s_waitcnt lgkmcnt(0)
	v_mul_f32_e32 v69, v69, v47
	v_fmac_f32_e32 v69, v68, v46
	v_fmac_f32_e32 v69, v70, v7
	v_fmac_f32_e32 v69, v71, v6
	v_add_f32_e32 v72, v72, v69
	ds_read_b128 v[68:71], v66 offset:320
	s_waitcnt lgkmcnt(0)
	v_mul_f32_e32 v69, v69, v55
	v_fmac_f32_e32 v69, v68, v54
	v_fmac_f32_e32 v69, v70, v44
	v_fmac_f32_e32 v69, v71, v45
	v_add_f32_e32 v72, v72, v69
	ds_read_b128 v[68:71], v66 offset:336
	s_waitcnt lgkmcnt(0)
	v_mul_f32_e32 v69, v69, v53
	v_fmac_f32_e32 v69, v68, v52
	v_fmac_f32_e32 v69, v70, v5
	v_fmac_f32_e32 v69, v71, v4
	v_add_f32_e32 v72, v72, v69
	ds_read_b128 v[68:71], v66 offset:384
	s_waitcnt lgkmcnt(0)
	v_mul_f32_e32 v69, v69, v61
	v_fmac_f32_e32 v69, v68, v60
	v_fmac_f32_e32 v69, v70, v50
	v_fmac_f32_e32 v69, v71, v51
	v_add_f32_e32 v72, v72, v69
	ds_read_b128 v[68:71], v66 offset:400
	s_waitcnt lgkmcnt(0)
	v_mul_f32_e32 v69, v69, v59
	v_fmac_f32_e32 v69, v68, v58
	v_fmac_f32_e32 v69, v70, v3
	v_fmac_f32_e32 v69, v71, v2
	v_add_f32_e32 v72, v72, v69
	ds_read_b128 v[68:71], v66 offset:448
	s_waitcnt lgkmcnt(0)
	v_mul_f32_e32 v69, v69, v65
	v_fmac_f32_e32 v69, v68, v64
	v_fmac_f32_e32 v69, v70, v56
	v_fmac_f32_e32 v69, v71, v57
	v_add_f32_e32 v72, v72, v69
	ds_read_b128 v[68:71], v66 offset:464
	s_waitcnt lgkmcnt(0)
	v_mul_f32_e32 v69, v69, v63
	v_fmac_f32_e32 v69, v68, v62
	v_fmac_f32_e32 v69, v70, v1
	v_fmac_f32_e32 v69, v71, v0
	v_add_f32_e32 v68, v72, v69
	ds_read_b128 v[70:73], v66 offset:512
	ds_bpermute_b32 v69, v170, v68
	s_waitcnt lgkmcnt(1)
	v_mul_f32_e32 v71, v71, v23
	v_fmac_f32_e32 v71, v70, v22
	v_fmac_f32_e32 v71, v72, v16
	v_fmac_f32_e32 v71, v73, v17
	v_add_f32_e32 v74, 0, v71
	ds_read_b128 v[70:73], v66 offset:528
	s_waitcnt lgkmcnt(0)
	v_mul_f32_e32 v71, v71, v21
	v_fmac_f32_e32 v71, v70, v20
	v_fmac_f32_e32 v71, v72, v15
	v_fmac_f32_e32 v71, v73, v14
	v_add_f32_e32 v74, v74, v71
	ds_read_b128 v[70:73], v66 offset:576
	s_waitcnt lgkmcnt(0)
	v_mul_f32_e32 v71, v71, v29
	v_fmac_f32_e32 v71, v70, v28
	v_fmac_f32_e32 v71, v72, v18
	v_fmac_f32_e32 v71, v73, v19
	v_add_f32_e32 v74, v74, v71
	ds_read_b128 v[70:73], v66 offset:592
	s_waitcnt lgkmcnt(0)
	v_mul_f32_e32 v71, v71, v27
	v_fmac_f32_e32 v71, v70, v26
	v_fmac_f32_e32 v71, v72, v13
	v_fmac_f32_e32 v71, v73, v12
	v_add_f32_e32 v74, v74, v71
	ds_read_b128 v[70:73], v66 offset:640
	s_waitcnt lgkmcnt(0)
	v_mul_f32_e32 v71, v71, v35
	v_fmac_f32_e32 v71, v70, v34
	v_fmac_f32_e32 v71, v72, v24
	v_fmac_f32_e32 v71, v73, v25
	v_add_f32_e32 v74, v74, v71
	ds_read_b128 v[70:73], v66 offset:656
	s_waitcnt lgkmcnt(0)
	v_mul_f32_e32 v71, v71, v33
	v_fmac_f32_e32 v71, v70, v32
	v_fmac_f32_e32 v71, v72, v11
	v_fmac_f32_e32 v71, v73, v10
	v_add_f32_e32 v74, v74, v71
	ds_read_b128 v[70:73], v66 offset:704
	s_waitcnt lgkmcnt(0)
	v_mul_f32_e32 v71, v71, v43
	v_fmac_f32_e32 v71, v70, v42
	v_fmac_f32_e32 v71, v72, v30
	v_fmac_f32_e32 v71, v73, v31
	v_add_f32_e32 v74, v74, v71
	ds_read_b128 v[70:73], v66 offset:720
	s_waitcnt lgkmcnt(0)
	v_mul_f32_e32 v71, v71, v41
	v_fmac_f32_e32 v71, v70, v40
	v_fmac_f32_e32 v71, v72, v9
	v_fmac_f32_e32 v71, v73, v8
	v_add_f32_e32 v74, v74, v71
	ds_read_b128 v[70:73], v66 offset:768
	s_waitcnt lgkmcnt(0)
	v_mul_f32_e32 v71, v71, v49
	v_fmac_f32_e32 v71, v70, v48
	v_fmac_f32_e32 v71, v72, v38
	v_fmac_f32_e32 v71, v73, v39
	v_add_f32_e32 v74, v74, v71
	ds_read_b128 v[70:73], v66 offset:784
	s_waitcnt lgkmcnt(0)
	v_mul_f32_e32 v71, v71, v47
	v_fmac_f32_e32 v71, v70, v46
	v_fmac_f32_e32 v71, v72, v7
	v_fmac_f32_e32 v71, v73, v6
	v_add_f32_e32 v74, v74, v71
	ds_read_b128 v[70:73], v66 offset:832
	s_waitcnt lgkmcnt(0)
; #define LAS __attribute__((address_space(3)))
; __device__ __forceinline__ float bf2f(unsigned short v) { return __uint_as_float(((unsigned)v) << 16); }
; template <int DQK, bool MOBA>
; __device__ __forceinline__ void attn_unit(const Args& A, int b, int h, int qb, lptr lds) {
;     ...
;             float g[7];
; #pragma unroll
;             for (int j = 0; j < 7; ++j) {
;                 float a = 0.f;
;                 if (j < own) {
; #pragma unroll
;                     for (int s = 0; s < NS; ++s) {
;                         const f32x4 k0 = *(const LAS f32x4*)(km + j * 128 + 16 * s + 8 * hi), k1 = *(const LAS f32x4*)(km + j * 128 + 16 * s + 8 * hi + 4);
;                         a += bf2f((unsigned short)qf[s][0]) * k0[0] + bf2f((unsigned short)qf[s][1]) * k0[1] + bf2f((unsigned short)qf[s][2]) * k0[2] + bf2f((unsigned short)qf[s][3]) * k0[3];
;                         a += bf2f((unsigned short)qf[s][4]) * k1[0] + bf2f((unsigned short)qf[s][5]) * k1[1] + bf2f((unsigned short)qf[s][6]) * k1[2] + bf2f((unsigned short)qf[s][7]) * k1[3];
;                     }
;                 }
;                 a += __shfl_xor(a, 32);
;                 g[j] = a;
;             }
	v_mul_f32_e32 v71, v71, v55
	v_fmac_f32_e32 v71, v70, v54
	v_fmac_f32_e32 v71, v72, v44
	v_fmac_f32_e32 v71, v73, v45
	v_add_f32_e32 v74, v74, v71
	ds_read_b128 v[70:73], v66 offset:848
	s_waitcnt lgkmcnt(0)
	v_mul_f32_e32 v71, v71, v53
	v_fmac_f32_e32 v71, v70, v52
	v_fmac_f32_e32 v71, v72, v5
	v_fmac_f32_e32 v71, v73, v4
	v_add_f32_e32 v74, v74, v71
	ds_read_b128 v[70:73], v66 offset:896
	s_waitcnt lgkmcnt(0)
	v_mul_f32_e32 v71, v71, v61
	v_fmac_f32_e32 v71, v70, v60
	v_fmac_f32_e32 v71, v72, v50
	v_fmac_f32_e32 v71, v73, v51
	v_add_f32_e32 v74, v74, v71
	ds_read_b128 v[70:73], v66 offset:912
	s_waitcnt lgkmcnt(0)
	v_mul_f32_e32 v71, v71, v59
	v_fmac_f32_e32 v71, v70, v58
	v_fmac_f32_e32 v71, v72, v3
	v_fmac_f32_e32 v71, v73, v2
	v_add_f32_e32 v74, v74, v71
	ds_read_b128 v[70:73], v66 offset:960
	s_waitcnt lgkmcnt(0)
	v_mul_f32_e32 v71, v71, v65
	v_fmac_f32_e32 v71, v70, v64
	v_fmac_f32_e32 v71, v72, v56
	v_fmac_f32_e32 v71, v73, v57
	v_add_f32_e32 v74, v74, v71
	ds_read_b128 v[70:73], v66 offset:976
	s_waitcnt lgkmcnt(0)
	v_mul_f32_e32 v71, v71, v63
	v_fmac_f32_e32 v71, v70, v62
	v_fmac_f32_e32 v71, v72, v1
	v_fmac_f32_e32 v71, v73, v0
	v_add_f32_e32 v70, v74, v71
	ds_read_b128 v[72:75], v66 offset:1024
	ds_bpermute_b32 v71, v170, v70
	s_waitcnt lgkmcnt(1)
	v_mul_f32_e32 v73, v73, v23
	v_fmac_f32_e32 v73, v72, v22
	v_fmac_f32_e32 v73, v74, v16
	v_fmac_f32_e32 v73, v75, v17
	v_add_f32_e32 v76, 0, v73
	ds_read_b128 v[72:75], v66 offset:1040
	s_waitcnt lgkmcnt(0)
	v_mul_f32_e32 v73, v73, v21
	v_fmac_f32_e32 v73, v72, v20
	v_fmac_f32_e32 v73, v74, v15
	v_fmac_f32_e32 v73, v75, v14
	v_add_f32_e32 v76, v76, v73
	ds_read_b128 v[72:75], v66 offset:1088
	s_waitcnt lgkmcnt(0)
	v_mul_f32_e32 v73, v73, v29
	v_fmac_f32_e32 v73, v72, v28
	v_fmac_f32_e32 v73, v74, v18
	v_fmac_f32_e32 v73, v75, v19
	v_add_f32_e32 v76, v76, v73
	ds_read_b128 v[72:75], v66 offset:1104
	s_waitcnt lgkmcnt(0)
	v_mul_f32_e32 v73, v73, v27
	v_fmac_f32_e32 v73, v72, v26
	v_fmac_f32_e32 v73, v74, v13
	v_fmac_f32_e32 v73, v75, v12
	v_add_f32_e32 v76, v76, v73
	ds_read_b128 v[72:75], v66 offset:1152
	s_waitcnt lgkmcnt(0)
	v_mul_f32_e32 v73, v73, v35
	v_fmac_f32_e32 v73, v72, v34
	v_fmac_f32_e32 v73, v74, v24
	v_fmac_f32_e32 v73, v75, v25
	v_add_f32_e32 v76, v76, v73
	ds_read_b128 v[72:75], v66 offset:1168
	s_waitcnt lgkmcnt(0)
	v_mul_f32_e32 v73, v73, v33
	v_fmac_f32_e32 v73, v72, v32
	v_fmac_f32_e32 v73, v74, v11
	v_fmac_f32_e32 v73, v75, v10
	v_add_f32_e32 v76, v76, v73
	ds_read_b128 v[72:75], v66 offset:1216
	s_waitcnt lgkmcnt(0)
	v_mul_f32_e32 v73, v73, v43
	v_fmac_f32_e32 v73, v72, v42
	v_fmac_f32_e32 v73, v74, v30
	v_fmac_f32_e32 v73, v75, v31
	v_add_f32_e32 v76, v76, v73
	ds_read_b128 v[72:75], v66 offset:1232
	s_waitcnt lgkmcnt(0)
	v_mul_f32_e32 v73, v73, v41
	v_fmac_f32_e32 v73, v72, v40
	v_fmac_f32_e32 v73, v74, v9
	v_fmac_f32_e32 v73, v75, v8
	v_add_f32_e32 v76, v76, v73
	ds_read_b128 v[72:75], v66 offset:1280
	s_waitcnt lgkmcnt(0)
	v_mul_f32_e32 v73, v73, v49
	v_fmac_f32_e32 v73, v72, v48
	v_fmac_f32_e32 v73, v74, v38
	v_fmac_f32_e32 v73, v75, v39
	v_add_f32_e32 v76, v76, v73
	ds_read_b128 v[72:75], v66 offset:1296
	s_waitcnt lgkmcnt(0)
	v_mul_f32_e32 v73, v73, v47
	v_fmac_f32_e32 v73, v72, v46
	v_fmac_f32_e32 v73, v74, v7
	v_fmac_f32_e32 v73, v75, v6
	v_add_f32_e32 v76, v76, v73
	ds_read_b128 v[72:75], v66 offset:1344
	s_waitcnt lgkmcnt(0)
	v_mul_f32_e32 v73, v73, v55
	v_fmac_f32_e32 v73, v72, v54
	v_fmac_f32_e32 v73, v74, v44
	v_fmac_f32_e32 v73, v75, v45
	v_add_f32_e32 v76, v76, v73
	ds_read_b128 v[72:75], v66 offset:1360
	s_waitcnt lgkmcnt(0)
	v_mul_f32_e32 v73, v73, v53
	v_fmac_f32_e32 v73, v72, v52
	v_fmac_f32_e32 v73, v74, v5
	v_fmac_f32_e32 v73, v75, v4
	v_add_f32_e32 v76, v76, v73
	ds_read_b128 v[72:75], v66 offset:1408
	s_waitcnt lgkmcnt(0)
	v_mul_f32_e32 v73, v73, v61
	v_fmac_f32_e32 v73, v72, v60
	v_fmac_f32_e32 v73, v74, v50
	v_fmac_f32_e32 v73, v75, v51
	v_add_f32_e32 v76, v76, v73
	ds_read_b128 v[72:75], v66 offset:1424
	s_waitcnt lgkmcnt(0)
	v_mul_f32_e32 v73, v73, v59
	v_fmac_f32_e32 v73, v72, v58
	v_fmac_f32_e32 v73, v74, v3
	v_fmac_f32_e32 v73, v75, v2
	v_add_f32_e32 v76, v76, v73
	ds_read_b128 v[72:75], v66 offset:1472
	s_waitcnt lgkmcnt(0)
	v_mul_f32_e32 v73, v73, v65
	v_fmac_f32_e32 v73, v72, v64
	v_fmac_f32_e32 v73, v74, v56
	v_fmac_f32_e32 v73, v75, v57
	v_add_f32_e32 v76, v76, v73
	ds_read_b128 v[72:75], v66 offset:1488
	s_waitcnt lgkmcnt(0)
	v_mul_f32_e32 v73, v73, v63
	v_fmac_f32_e32 v73, v72, v62
	v_fmac_f32_e32 v73, v74, v1
	v_fmac_f32_e32 v73, v75, v0
	v_add_f32_e32 v72, v76, v73
	ds_read_b128 v[74:77], v66 offset:1536
	ds_bpermute_b32 v73, v170, v72
	s_waitcnt lgkmcnt(1)
	v_mul_f32_e32 v75, v75, v23
	v_fmac_f32_e32 v75, v74, v22
	v_fmac_f32_e32 v75, v76, v16
	v_fmac_f32_e32 v75, v77, v17
	v_add_f32_e32 v78, 0, v75
	ds_read_b128 v[74:77], v66 offset:1552
	s_waitcnt lgkmcnt(0)
	v_mul_f32_e32 v75, v75, v21
	v_fmac_f32_e32 v75, v74, v20
	v_fmac_f32_e32 v75, v76, v15
	v_fmac_f32_e32 v75, v77, v14
	v_add_f32_e32 v78, v78, v75
	ds_read_b128 v[74:77], v66 offset:1600
	s_waitcnt lgkmcnt(0)
	v_mul_f32_e32 v75, v75, v29
	v_fmac_f32_e32 v75, v74, v28
	v_fmac_f32_e32 v75, v76, v18
	v_fmac_f32_e32 v75, v77, v19
	v_add_f32_e32 v78, v78, v75
	ds_read_b128 v[74:77], v66 offset:1616
	s_waitcnt lgkmcnt(0)
	v_mul_f32_e32 v75, v75, v27
	v_fmac_f32_e32 v75, v74, v26
	v_fmac_f32_e32 v75, v76, v13
	v_fmac_f32_e32 v75, v77, v12
	v_add_f32_e32 v78, v78, v75
	ds_read_b128 v[74:77], v66 offset:1664
	s_waitcnt lgkmcnt(0)
	v_mul_f32_e32 v75, v75, v35
	v_fmac_f32_e32 v75, v74, v34
	v_fmac_f32_e32 v75, v76, v24
	v_fmac_f32_e32 v75, v77, v25
	v_add_f32_e32 v78, v78, v75
	ds_read_b128 v[74:77], v66 offset:1680
	s_waitcnt lgkmcnt(0)
; #define LAS __attribute__((address_space(3)))
; __device__ __forceinline__ float bf2f(unsigned short v) { return __uint_as_float(((unsigned)v) << 16); }
; template <int DQK, bool MOBA>
; __device__ __forceinline__ void attn_unit(const Args& A, int b, int h, int qb, lptr lds) {
;     ...
;             float g[7];
; #pragma unroll
;             for (int j = 0; j < 7; ++j) {
;                 float a = 0.f;
;                 if (j < own) {
; #pragma unroll
;                     for (int s = 0; s < NS; ++s) {
;                         const f32x4 k0 = *(const LAS f32x4*)(km + j * 128 + 16 * s + 8 * hi), k1 = *(const LAS f32x4*)(km + j * 128 + 16 * s + 8 * hi + 4);
;                         a += bf2f((unsigned short)qf[s][0]) * k0[0] + bf2f((unsigned short)qf[s][1]) * k0[1] + bf2f((unsigned short)qf[s][2]) * k0[2] + bf2f((unsigned short)qf[s][3]) * k0[3];
;                         a += bf2f((unsigned short)qf[s][4]) * k1[0] + bf2f((unsigned short)qf[s][5]) * k1[1] + bf2f((unsigned short)qf[s][6]) * k1[2] + bf2f((unsigned short)qf[s][7]) * k1[3];
;                     }
;                 }
;                 a += __shfl_xor(a, 32);
;                 g[j] = a;
;             }
	v_mul_f32_e32 v75, v75, v33
	v_fmac_f32_e32 v75, v74, v32
	v_fmac_f32_e32 v75, v76, v11
	v_fmac_f32_e32 v75, v77, v10
	v_add_f32_e32 v78, v78, v75
	ds_read_b128 v[74:77], v66 offset:1728
	s_waitcnt lgkmcnt(0)
	v_mul_f32_e32 v75, v75, v43
	v_fmac_f32_e32 v75, v74, v42
	v_fmac_f32_e32 v75, v76, v30
	v_fmac_f32_e32 v75, v77, v31
	v_add_f32_e32 v78, v78, v75
	ds_read_b128 v[74:77], v66 offset:1744
	s_waitcnt lgkmcnt(0)
	v_mul_f32_e32 v75, v75, v41
	v_fmac_f32_e32 v75, v74, v40
	v_fmac_f32_e32 v75, v76, v9
	v_fmac_f32_e32 v75, v77, v8
	v_add_f32_e32 v78, v78, v75
	ds_read_b128 v[74:77], v66 offset:1792
	s_waitcnt lgkmcnt(0)
	v_mul_f32_e32 v75, v75, v49
	v_fmac_f32_e32 v75, v74, v48
	v_fmac_f32_e32 v75, v76, v38
	v_fmac_f32_e32 v75, v77, v39
	v_add_f32_e32 v78, v78, v75
	ds_read_b128 v[74:77], v66 offset:1808
	s_waitcnt lgkmcnt(0)
	v_mul_f32_e32 v75, v75, v47
	v_fmac_f32_e32 v75, v74, v46
	v_fmac_f32_e32 v75, v76, v7
	v_fmac_f32_e32 v75, v77, v6
	v_add_f32_e32 v78, v78, v75
	ds_read_b128 v[74:77], v66 offset:1856
	s_waitcnt lgkmcnt(0)
	v_mul_f32_e32 v75, v75, v55
	v_fmac_f32_e32 v75, v74, v54
	v_fmac_f32_e32 v75, v76, v44
	v_fmac_f32_e32 v75, v77, v45
	v_add_f32_e32 v78, v78, v75
	ds_read_b128 v[74:77], v66 offset:1872
	s_waitcnt lgkmcnt(0)
	v_mul_f32_e32 v75, v75, v53
	v_fmac_f32_e32 v75, v74, v52
	v_fmac_f32_e32 v75, v76, v5
	v_fmac_f32_e32 v75, v77, v4
	v_add_f32_e32 v78, v78, v75
	ds_read_b128 v[74:77], v66 offset:1920
	s_waitcnt lgkmcnt(0)
	v_mul_f32_e32 v75, v75, v61
	v_fmac_f32_e32 v75, v74, v60
	v_fmac_f32_e32 v75, v76, v50
	v_fmac_f32_e32 v75, v77, v51
	v_add_f32_e32 v78, v78, v75
	ds_read_b128 v[74:77], v66 offset:1936
	s_waitcnt lgkmcnt(0)
	v_mul_f32_e32 v75, v75, v59
	v_fmac_f32_e32 v75, v74, v58
	v_fmac_f32_e32 v75, v76, v3
	v_fmac_f32_e32 v75, v77, v2
	v_add_f32_e32 v78, v78, v75
	ds_read_b128 v[74:77], v66 offset:1984
	s_waitcnt lgkmcnt(0)
	v_mul_f32_e32 v75, v75, v65
	v_fmac_f32_e32 v75, v74, v64
	v_fmac_f32_e32 v75, v76, v56
	v_fmac_f32_e32 v75, v77, v57
	v_add_f32_e32 v78, v78, v75
	ds_read_b128 v[74:77], v66 offset:2000
	s_waitcnt lgkmcnt(0)
	v_mul_f32_e32 v75, v75, v63
	v_fmac_f32_e32 v75, v74, v62
	v_fmac_f32_e32 v75, v76, v1
	v_fmac_f32_e32 v75, v77, v0
	v_add_f32_e32 v74, v78, v75
	ds_bpermute_b32 v75, v170, v74
	v_mov_b32_e32 v76, 0
	s_cbranch_scc1 .LBB0_764
; #define LAS __attribute__((address_space(3)))
; __device__ __forceinline__ float bf2f(unsigned short v) { return __uint_as_float(((unsigned)v) << 16); }
; template <int DQK, bool MOBA>
; __device__ __forceinline__ void attn_unit(const Args& A, int b, int h, int qb, lptr lds) {
;     ...
;             float g[7];
; #pragma unroll
;             for (int j = 0; j < 7; ++j) {
;                 float a = 0.f;
;                 if (j < own) {
; #pragma unroll
;                     for (int s = 0; s < NS; ++s) {
;                         const f32x4 k0 = *(const LAS f32x4*)(km + j * 128 + 16 * s + 8 * hi), k1 = *(const LAS f32x4*)(km + j * 128 + 16 * s + 8 * hi + 4);
;                         a += bf2f((unsigned short)qf[s][0]) * k0[0] + bf2f((unsigned short)qf[s][1]) * k0[1] + bf2f((unsigned short)qf[s][2]) * k0[2] + bf2f((unsigned short)qf[s][3]) * k0[3];
;                         a += bf2f((unsigned short)qf[s][4]) * k1[0] + bf2f((unsigned short)qf[s][5]) * k1[1] + bf2f((unsigned short)qf[s][6]) * k1[2] + bf2f((unsigned short)qf[s][7]) * k1[3];
;                     }
;                 }
;                 a += __shfl_xor(a, 32);
;                 g[j] = a;
;             }
	ds_read_b128 v[76:79], v66 offset:2048
	ds_read_b128 v[90:93], v66 offset:2064
	v_mov_b32_e32 v96, v34
	v_mov_b32_e32 v97, v32
	s_waitcnt lgkmcnt(1)
	v_mul_f32_e32 v77, v77, v23
	v_fmac_f32_e32 v77, v76, v22
	v_fmac_f32_e32 v77, v78, v16
	v_fmac_f32_e32 v77, v79, v17
	v_add_f32_e32 v76, 0, v77
	s_waitcnt lgkmcnt(0)
	v_mul_f32_e32 v77, v91, v21
	v_fmac_f32_e32 v77, v90, v20
	v_fmac_f32_e32 v77, v92, v15
	v_fmac_f32_e32 v77, v93, v14
	v_add_f32_e32 v94, v76, v77
	ds_read_b128 v[76:79], v66 offset:2112
	ds_read_b128 v[90:93], v66 offset:2128
	s_waitcnt lgkmcnt(1)
	v_mul_f32_e32 v77, v77, v29
	v_fmac_f32_e32 v77, v76, v28
	v_fmac_f32_e32 v77, v78, v18
	v_fmac_f32_e32 v77, v79, v19
	v_add_f32_e32 v76, v94, v77
	s_waitcnt lgkmcnt(0)
	v_mul_f32_e32 v77, v91, v27
	v_fmac_f32_e32 v77, v90, v26
	v_fmac_f32_e32 v77, v92, v13
	v_fmac_f32_e32 v77, v93, v12
	v_add_f32_e32 v98, v76, v77
	ds_read_b128 v[76:79], v66 offset:2176
	ds_read_b128 v[90:93], v66 offset:2192
	s_waitcnt lgkmcnt(1)
	v_mov_b32_e32 v94, v76
	s_waitcnt lgkmcnt(0)
	v_mov_b32_e32 v95, v90
	v_mov_b32_e32 v90, v77
	v_mov_b32_e32 v76, v35
	v_mov_b32_e32 v77, v33
	v_pk_mul_f32 v[76:77], v[90:91], v[76:77]
	v_mov_b32_e32 v90, v78
	v_pk_fma_f32 v[76:77], v[94:95], v[96:97], v[76:77]
	v_mov_b32_e32 v91, v92
	v_mov_b32_e32 v94, v24
	v_mov_b32_e32 v95, v11
	v_pk_fma_f32 v[76:77], v[90:91], v[94:95], v[76:77]
	v_mov_b32_e32 v92, v79
	v_pk_mov_b32 v[78:79], v[24:25], v[10:11] op_sel:[1,0]
	v_mov_b32_e32 v96, v42
	v_pk_fma_f32 v[76:77], v[92:93], v[78:79], v[76:77]
	v_mov_b32_e32 v97, v40
	v_add_f32_e32 v76, v98, v76
	v_add_f32_e32 v98, v76, v77
	ds_read_b128 v[76:79], v66 offset:2240
	ds_read_b128 v[90:93], v66 offset:2256
	s_waitcnt lgkmcnt(1)
	v_mov_b32_e32 v94, v76
	s_waitcnt lgkmcnt(0)
	v_mov_b32_e32 v95, v90
	v_mov_b32_e32 v90, v77
	v_mov_b32_e32 v76, v43
	v_mov_b32_e32 v77, v41
	v_pk_mul_f32 v[76:77], v[90:91], v[76:77]
	v_mov_b32_e32 v90, v78
	v_pk_fma_f32 v[76:77], v[94:95], v[96:97], v[76:77]
	v_mov_b32_e32 v91, v92
	v_mov_b32_e32 v94, v30
	v_mov_b32_e32 v95, v9
	v_pk_fma_f32 v[76:77], v[90:91], v[94:95], v[76:77]
	v_mov_b32_e32 v92, v79
	v_pk_mov_b32 v[78:79], v[30:31], v[8:9] op_sel:[1,0]
	v_mov_b32_e32 v96, v48
	v_pk_fma_f32 v[76:77], v[92:93], v[78:79], v[76:77]
	v_mov_b32_e32 v97, v46
	v_add_f32_e32 v76, v98, v76
	v_add_f32_e32 v98, v76, v77
	ds_read_b128 v[76:79], v66 offset:2304
	ds_read_b128 v[90:93], v66 offset:2320
	s_waitcnt lgkmcnt(1)
	v_mov_b32_e32 v94, v76
	s_waitcnt lgkmcnt(0)
	v_mov_b32_e32 v95, v90
	v_mov_b32_e32 v90, v77
	v_mov_b32_e32 v76, v49
	v_mov_b32_e32 v77, v47
	v_pk_mul_f32 v[76:77], v[90:91], v[76:77]
	v_mov_b32_e32 v90, v78
	v_pk_fma_f32 v[76:77], v[94:95], v[96:97], v[76:77]
	v_mov_b32_e32 v91, v92
	v_mov_b32_e32 v94, v38
	v_mov_b32_e32 v95, v7
	v_pk_fma_f32 v[76:77], v[90:91], v[94:95], v[76:77]
	v_mov_b32_e32 v92, v79
	v_pk_mov_b32 v[78:79], v[38:39], v[6:7] op_sel:[1,0]
	v_mov_b32_e32 v96, v54
	v_pk_fma_f32 v[76:77], v[92:93], v[78:79], v[76:77]
	v_mov_b32_e32 v97, v52
	v_add_f32_e32 v76, v98, v76
	v_add_f32_e32 v98, v76, v77
	ds_read_b128 v[76:79], v66 offset:2368
	ds_read_b128 v[90:93], v66 offset:2384
	s_waitcnt lgkmcnt(1)
	v_mov_b32_e32 v94, v76
	s_waitcnt lgkmcnt(0)
	v_mov_b32_e32 v95, v90
	v_mov_b32_e32 v90, v77
	v_mov_b32_e32 v76, v55
	v_mov_b32_e32 v77, v53
	v_pk_mul_f32 v[76:77], v[90:91], v[76:77]
	v_mov_b32_e32 v90, v78
	v_pk_fma_f32 v[76:77], v[94:95], v[96:97], v[76:77]
	v_mov_b32_e32 v91, v92
	v_mov_b32_e32 v94, v44
	v_mov_b32_e32 v95, v5
	v_pk_fma_f32 v[76:77], v[90:91], v[94:95], v[76:77]
	v_mov_b32_e32 v92, v79
	v_pk_mov_b32 v[78:79], v[44:45], v[4:5] op_sel:[1,0]
	v_mov_b32_e32 v96, v60
	v_pk_fma_f32 v[76:77], v[92:93], v[78:79], v[76:77]
	v_mov_b32_e32 v97, v58
	v_add_f32_e32 v76, v98, v76
	v_add_f32_e32 v98, v76, v77
	ds_read_b128 v[76:79], v66 offset:2432
	ds_read_b128 v[90:93], v66 offset:2448
	s_waitcnt lgkmcnt(1)
	v_mov_b32_e32 v94, v76
	s_waitcnt lgkmcnt(0)
	v_mov_b32_e32 v95, v90
	v_mov_b32_e32 v90, v77
	v_mov_b32_e32 v76, v61
	v_mov_b32_e32 v77, v59
	v_pk_mul_f32 v[76:77], v[90:91], v[76:77]
	v_mov_b32_e32 v90, v78
	v_pk_fma_f32 v[76:77], v[94:95], v[96:97], v[76:77]
	v_mov_b32_e32 v91, v92
	v_mov_b32_e32 v94, v50
	v_mov_b32_e32 v95, v3
	v_pk_fma_f32 v[76:77], v[90:91], v[94:95], v[76:77]
	v_mov_b32_e32 v92, v79
	v_pk_mov_b32 v[78:79], v[50:51], v[2:3] op_sel:[1,0]
	v_mov_b32_e32 v96, v64
	v_pk_fma_f32 v[76:77], v[92:93], v[78:79], v[76:77]
	v_mov_b32_e32 v97, v62
	v_add_f32_e32 v76, v98, v76
	v_add_f32_e32 v98, v76, v77
	ds_read_b128 v[76:79], v66 offset:2496
	ds_read_b128 v[90:93], v66 offset:2512
	s_waitcnt lgkmcnt(1)
	v_mov_b32_e32 v94, v76
	s_waitcnt lgkmcnt(0)
	v_mov_b32_e32 v95, v90
	v_mov_b32_e32 v90, v77
	v_mov_b32_e32 v76, v65
	v_mov_b32_e32 v77, v63
	v_pk_mul_f32 v[76:77], v[90:91], v[76:77]
	v_mov_b32_e32 v90, v78
	v_pk_fma_f32 v[76:77], v[94:95], v[96:97], v[76:77]
	v_mov_b32_e32 v91, v92
	v_mov_b32_e32 v94, v56
	v_mov_b32_e32 v95, v1
	v_pk_fma_f32 v[76:77], v[90:91], v[94:95], v[76:77]
	v_mov_b32_e32 v92, v79
	v_pk_mov_b32 v[78:79], v[56:57], v[0:1] op_sel:[1,0]
	s_nop 0
	v_pk_fma_f32 v[76:77], v[92:93], v[78:79], v[76:77]
	s_nop 0
	v_add_f32_e32 v76, v98, v76
	v_add_f32_e32 v76, v76, v77

; template <int DQK, bool MOBA>
; __device__ __forceinline__ void attn_unit(const Args& A, int b, int h, int qb, lptr lds) {
;     ...
;         pq = A.pos[qrow];
;     ...
;     f32x16 o[4];
; #pragma unroll
;     for (int d = 0; d < 4; ++d)
; #pragma unroll
;         for (int r = 0; r < 16; ++r) o[d][r] = 0.f;
;     float lrow = 0.f;
;     ATT_LOAD(0); ATT_WRITE(0);
;     if (NT > 1) ATT_LOAD(1);
.LBB0_775:
	s_or_b64 exec, exec, s[0:1]
	s_movk_i32 s0, 0x110
	v_mul_lo_u32 v167, v22, s0
	v_add3_u32 v26, 0, v167, v166
	s_waitcnt vmcnt(2)
	ds_write_b128 v26, v[0:3]
	ds_write_b128 v26, v[4:7] offset:8704
	v_mad_u64_u32 v[0:1], s[0:1], v22, 48, v[26:27]
	s_waitcnt vmcnt(1)
	ds_write_b128 v0, v[8:11] offset:34816
	v_mul_lo_u32 v0, v24, 48
	s_movk_i32 s0, 0x2200
	v_add3_u32 v0, v26, s0, v0
	s_waitcnt vmcnt(0)
	ds_write_b128 v0, v[12:15] offset:34816
	v_lshlrev_b32_e32 v171, 2, v171
	v_add_u32_e32 v171, 0x12a00, v171
	s_and_saveexec_b64 s[0:1], s[40:41]
	v_lshl_add_u32 v0, v162, 2, 0
	v_add_u32_e32 v0, 0x12800, v0
	v_lshlrev_b32_e32 v173, 2, v173
	ds_write_b32 v0, v173
	s_or_b64 exec, exec, s[0:1]
	s_or_b32 s0, s42, 64
	s_mul_i32 s7, s0, 0x1800
	s_mul_hi_i32 s6, s0, 0x1800
	s_add_u32 s0, s95, s7
	s_addc_u32 s1, s8, s6
	s_add_u32 s0, s0, s4
	v_lshlrev_b32_e32 v2, 3, v23
	s_addc_u32 s1, s1, s5
	v_lshl_add_u64 v[0:1], s[0:1], 0, v[164:165]
	v_lshlrev_b32_e32 v180, 1, v2
	v_lshl_add_u64 v[2:3], s[0:1], 0, v[168:169]
	s_add_u32 s0, s9, s7
	s_addc_u32 s1, s10, s6
	s_add_u32 s0, s0, s4
	v_lshl_add_u64 v[0:1], v[0:1], 0, v[180:181]
	s_addc_u32 s1, s1, s5
	v_lshl_add_u64 v[2:3], v[2:3], 0, v[180:181]
	global_load_dwordx4 v[144:147], v[0:1], off
	global_load_dwordx4 v[148:151], v[2:3], off
	v_lshl_add_u64 v[0:1], s[0:1], 0, v[164:165]
	v_lshl_add_u64 v[0:1], v[0:1], 0, v[180:181]
	v_lshl_add_u64 v[2:3], s[0:1], 0, v[168:169]
	v_lshl_add_u64 v[2:3], v[2:3], 0, v[180:181]
	global_load_dwordx4 v[152:155], v[0:1], off
	global_load_dwordx4 v[156:159], v[2:3], off
	s_and_saveexec_b64 s[0:1], s[40:41]
	s_cbranch_execz .LBB0_779
	s_ashr_i32 s43, s42, 31
	v_lshl_add_u64 v[0:1], s[42:43], 0, v[162:163]
	v_lshl_add_u64 v[0:1], v[0:1], 2, s[54:55]
	global_load_dword v173, v[0:1], off offset:256

; template <int DQK, bool MOBA>
; __device__ __forceinline__ void attn_unit(const Args& A, int b, int h, int qb, lptr lds) {
;     ...
;         if (t + 1 < NT) { ATT_WRITE(buf ^ 1); if (t + 2 < NT) ATT_LOAD(t + 2); }
.LBB0_782:
	s_add_i32 s6, s15, -2
	s_and_b32 s24, s6, 1
	s_add_i32 s0, s15, -1
	s_cmp_ge_u32 s0, s19
	s_cbranch_scc1 .LBB0_789
	s_xor_b32 s4, s24, 1
	s_mul_i32 s0, s4, 0x4400
	s_add_i32 s0, s0, 0
	s_mul_i32 s1, s4, 0xc00
	v_add3_u32 v80, s0, v167, v166
	s_add_i32 s1, s0, s1
	s_waitcnt vmcnt(3)
	ds_write_b128 v80, v[144:147]
	v_add3_u32 v80, s0, v163, v166
	s_waitcnt vmcnt(2)
	ds_write_b128 v80, v[148:151]
	v_add3_u32 v80, s1, v174, v166
	s_waitcnt vmcnt(1)
	ds_write_b128 v80, v[152:155] offset:34816
	v_add3_u32 v80, s1, v175, v166
	s_waitcnt vmcnt(0)
	ds_write_b128 v80, v[156:159] offset:34816
	s_and_saveexec_b64 s[0:1], s[40:41]
	v_lshl_add_u32 v80, s4, 8, v178
	v_lshlrev_b32_e32 v173, 2, v173
	ds_write_b32 v80, v173
	s_or_b64 exec, exec, s[0:1]
	s_cmp_ge_u32 s15, s19
	s_cbranch_scc1 .LBB0_789
	s_add_i32 s0, s18, s15
	s_add_i32 s1, s15, -4
	s_cmp_lt_u32 s6, 2
	s_cselect_b32 s0, s0, s1
	s_lshl_b32 s4, s0, 6
	s_add_i32 s4, s4, s70
	s_mul_i32 s7, s4, 0x1800
	s_mul_hi_i32 s5, s4, 0x1800
	s_add_u32 s0, s20, s7
	s_addc_u32 s1, s21, s5
	v_lshl_add_u64 v[80:81], s[0:1], 0, v[164:165]
	v_lshl_add_u64 v[82:83], s[0:1], 0, v[168:169]
	s_add_u32 s0, s22, s7
	v_lshl_add_u64 v[80:81], v[80:81], 0, v[180:181]
	s_addc_u32 s1, s23, s5
	v_lshl_add_u64 v[82:83], v[82:83], 0, v[180:181]
	global_load_dwordx4 v[144:147], v[80:81], off
	global_load_dwordx4 v[148:151], v[82:83], off
	v_lshl_add_u64 v[80:81], s[0:1], 0, v[164:165]
	v_lshl_add_u64 v[80:81], v[80:81], 0, v[180:181]
	v_lshl_add_u64 v[82:83], s[0:1], 0, v[168:169]
	v_lshl_add_u64 v[82:83], v[82:83], 0, v[180:181]
	global_load_dwordx4 v[152:155], v[80:81], off
	global_load_dwordx4 v[156:159], v[82:83], off
	s_and_saveexec_b64 s[0:1], s[40:41]
	s_cbranch_execz .LBB0_788
	v_add_u32_e32 v80, s4, v162
	v_ashrrev_i32_e32 v81, 31, v80
	v_lshl_add_u64 v[80:81], v[80:81], 2, s[54:55]
	global_load_dword v173, v[80:81], off

; #define LAS __attribute__((address_space(3)))
; #define MFMA32(a, b, c) __builtin_amdgcn_mfma_f32_32x32x16_bf16((a), (b), (c), 0, 0, 0)
; template <int DQK, bool MOBA>
; __device__ __forceinline__ void attn_unit(const Args& A, int b, int h, int qb, lptr lds) {
;     ...
;                 bf16x8 ka[2][2], kc[2][2];
; #pragma unroll
;                 for (int i = 0; i < 2; ++i) { ka[0][i] = *(const LAS bf16x8*)(kb + 32 * i); kc[0][i] = *(const LAS bf16x8*)(kb + 32 * L::KROW + 32 * i); }
;                 __builtin_amdgcn_sched_barrier(0);
; #pragma unroll
;                 for (int sb = 0; sb < NS; sb += 2) {
;                     const int cur = (sb >> 1) & 1, nxt = cur ^ 1;
;                     if (sb + 2 < NS) {
; #pragma unroll
;                         for (int i = 0; i < 2; ++i) { ka[nxt][i] = *(const LAS bf16x8*)(kb + 32 * (sb + 2 + i)); kc[nxt][i] = *(const LAS bf16x8*)(kb + 32 * L::KROW + 32 * (sb + 2 + i)); }
;                     }
;                     __builtin_amdgcn_sched_barrier(0);
; #pragma unroll
;                     for (int i = 0; i < 2; ++i) { s0 = MFMA32(ka[cur][i], qf[sb + i], s0); s1 = MFMA32(kc[cur][i], qf[sb + i], s1); }
;                     __builtin_amdgcn_sched_barrier(0);
;                 }
;             }
;             if (MOBA) {
;                 const LAS int* pp = (const LAS int*)(lds + L::OFF_POS + buf * 256);
; #pragma unroll
;                 for (int a = 0; a < 4; ++a) {
;                     const i32x4 p0 = *(const LAS i32x4*)(pp + 8 * a + 4 * hi), p1 = *(const LAS i32x4*)(pp + 32 + 8 * a + 4 * hi);
;                     const int pa[4] = {p0.x, p0.y, p0.z, p0.w}, pb[4] = {p1.x, p1.y, p1.z, p1.w};
; #pragma unroll
;                     for (int e = 0; e < 4; ++e) {
;                         int d0 = pq - pa[e]; d0 = d0 < 0 ? 0 : (d0 > 1023 ? 1023 : d0);
;                         int d1 = pq - pb[e]; d1 = d1 < 0 ? 0 : (d1 > 1023 ? 1023 : d1);
;                         s0[4 * a + e] += lut[d0]; s1[4 * a + e] += lut[d1];
;                     }
;                 }
;                 if (!lsel) {
; #pragma unroll
;                     for (int r = 0; r < 16; ++r) { s0[r] = NEG; s1[r] = NEG; }
;                 }
;             }
.LBB0_794:
	s_mul_i32 s6, s24, 0x4400
	v_add_u32_e32 v203, s6, v179
	ds_read_b128 v[80:83], v203
	ds_read_b128 v[186:189], v203 offset:32
	ds_read_b128 v[190:193], v203 offset:8704
	ds_read_b128 v[194:197], v203 offset:8736
	s_or_b64 s[42:43], s[4:5], s[0:1]
	ds_read_b128 v[198:201], v203 offset:64
	ds_read_b128 v[210:213], v203 offset:96
	ds_read_b128 v[214:217], v203 offset:8768
	ds_read_b128 v[218:221], v203 offset:8800
	s_waitcnt lgkmcnt(7)
	v_mfma_f32_32x32x16_bf16 v[96:111], v[80:83], v[112:115], v[64:79]
	s_waitcnt lgkmcnt(5)
	v_mfma_f32_32x32x16_bf16 v[80:95], v[190:193], v[112:115], v[64:79]
	v_mfma_f32_32x32x16_bf16 v[96:111], v[186:189], v[116:119], v[96:111]
	s_waitcnt lgkmcnt(4)
	v_mfma_f32_32x32x16_bf16 v[80:95], v[194:197], v[116:119], v[80:95]
	ds_read_b128 v[186:189], v203 offset:128
	ds_read_b128 v[190:193], v203 offset:160
	ds_read_b128 v[194:197], v203 offset:8832
	ds_read_b128 v[222:225], v203 offset:8864
	s_waitcnt lgkmcnt(7)
	v_mfma_f32_32x32x16_bf16 v[96:111], v[198:201], v[120:123], v[96:111]
	s_waitcnt lgkmcnt(5)
	v_mfma_f32_32x32x16_bf16 v[80:95], v[214:217], v[120:123], v[80:95]
	v_mfma_f32_32x32x16_bf16 v[96:111], v[210:213], v[124:127], v[96:111]
	s_waitcnt lgkmcnt(4)
	v_mfma_f32_32x32x16_bf16 v[80:95], v[218:221], v[124:127], v[80:95]
	ds_read_b128 v[198:201], v203 offset:192
	ds_read_b128 v[210:213], v203 offset:224
	ds_read_b128 v[214:217], v203 offset:8896
	ds_read_b128 v[218:221], v203 offset:8928
	s_waitcnt lgkmcnt(7)
	v_mfma_f32_32x32x16_bf16 v[96:111], v[186:189], v[128:131], v[96:111]
	s_waitcnt lgkmcnt(5)
	v_mfma_f32_32x32x16_bf16 v[80:95], v[194:197], v[128:131], v[80:95]
	v_mfma_f32_32x32x16_bf16 v[96:111], v[190:193], v[132:135], v[96:111]
	s_waitcnt lgkmcnt(4)
	v_mfma_f32_32x32x16_bf16 v[80:95], v[222:225], v[132:135], v[80:95]
	s_waitcnt lgkmcnt(3)
	v_mfma_f32_32x32x16_bf16 v[96:111], v[198:201], v[136:139], v[96:111]
	s_waitcnt lgkmcnt(1)
	v_mfma_f32_32x32x16_bf16 v[80:95], v[214:217], v[136:139], v[80:95]
	v_mfma_f32_32x32x16_bf16 v[96:111], v[210:213], v[140:143], v[96:111]
	s_waitcnt lgkmcnt(0)
	v_mfma_f32_32x32x16_bf16 v[80:95], v[218:221], v[140:143], v[80:95]
	v_lshl_add_u32 v203, s24, 8, v185
	s_mov_b64 vcc, s[42:43]
	s_mov_b32 s0, 0x12a00
	ds_read_b128 v[186:189], v203
	ds_read_b128 v[190:193], v203 offset:32
	ds_read_b128 v[194:197], v203 offset:64
	ds_read_b128 v[198:201], v203 offset:96
	ds_read_b128 v[210:213], v203 offset:128
	ds_read_b128 v[214:217], v203 offset:160
	ds_read_b128 v[218:221], v203 offset:192
	ds_read_b128 v[222:225], v203 offset:224
	v_cndmask_b32_e32 v227, v229, v171, vcc
	v_cndmask_b32_e32 v228, v230, v208, vcc
	s_waitcnt lgkmcnt(7)
	v_sub_u32_e32 v186, v227, v186
	v_sub_u32_e32 v187, v227, v187
	v_sub_u32_e32 v188, v227, v188
	v_sub_u32_e32 v189, v227, v189
	v_med3_i32 v186, v186, s0, v228
	v_med3_i32 v187, v187, s0, v228
	v_med3_i32 v188, v188, s0, v228
	v_med3_i32 v189, v189, s0, v228
	s_waitcnt lgkmcnt(6)
	v_sub_u32_e32 v190, v227, v190
	v_sub_u32_e32 v191, v227, v191
	v_sub_u32_e32 v192, v227, v192
	v_sub_u32_e32 v193, v227, v193
	v_med3_i32 v190, v190, s0, v228
	v_med3_i32 v191, v191, s0, v228
	v_med3_i32 v192, v192, s0, v228
	v_med3_i32 v193, v193, s0, v228
	s_waitcnt lgkmcnt(5)
	v_sub_u32_e32 v194, v227, v194
	v_sub_u32_e32 v195, v227, v195
	v_sub_u32_e32 v196, v227, v196
	v_sub_u32_e32 v197, v227, v197
	v_med3_i32 v194, v194, s0, v228
	v_med3_i32 v195, v195, s0, v228
	v_med3_i32 v196, v196, s0, v228
	v_med3_i32 v197, v197, s0, v228
	s_waitcnt lgkmcnt(4)
	v_sub_u32_e32 v198, v227, v198
	v_sub_u32_e32 v199, v227, v199
	v_sub_u32_e32 v200, v227, v200
	v_sub_u32_e32 v201, v227, v201
	v_med3_i32 v198, v198, s0, v228
	v_med3_i32 v199, v199, s0, v228
	v_med3_i32 v200, v200, s0, v228
	v_med3_i32 v201, v201, s0, v228
	s_waitcnt lgkmcnt(3)
	v_sub_u32_e32 v210, v227, v210
	v_sub_u32_e32 v211, v227, v211
	v_sub_u32_e32 v212, v227, v212
	v_sub_u32_e32 v213, v227, v213
	v_med3_i32 v210, v210, s0, v228
	v_med3_i32 v211, v211, s0, v228
	v_med3_i32 v212, v212, s0, v228
	v_med3_i32 v213, v213, s0, v228
	s_waitcnt lgkmcnt(2)
	v_sub_u32_e32 v214, v227, v214
	v_sub_u32_e32 v215, v227, v215
	v_sub_u32_e32 v216, v227, v216
	v_sub_u32_e32 v217, v227, v217
	v_med3_i32 v214, v214, s0, v228
	v_med3_i32 v215, v215, s0, v228
	v_med3_i32 v216, v216, s0, v228
	v_med3_i32 v217, v217, s0, v228
	s_waitcnt lgkmcnt(1)
	v_sub_u32_e32 v218, v227, v218
	v_sub_u32_e32 v219, v227, v219
	v_sub_u32_e32 v220, v227, v220
	v_sub_u32_e32 v221, v227, v221
	v_med3_i32 v218, v218, s0, v228
	v_med3_i32 v219, v219, s0, v228
	v_med3_i32 v220, v220, s0, v228
	v_med3_i32 v221, v221, s0, v228
	s_waitcnt lgkmcnt(0)
	v_sub_u32_e32 v222, v227, v222
	v_sub_u32_e32 v223, v227, v223
	v_sub_u32_e32 v224, v227, v224
	v_sub_u32_e32 v225, v227, v225
	v_med3_i32 v222, v222, s0, v228
	v_med3_i32 v223, v223, s0, v228
	v_med3_i32 v224, v224, s0, v228
	v_med3_i32 v225, v225, s0, v228
	ds_read_b32 v220, v220
	ds_read_b32 v210, v210
	ds_read_b32 v200, v200
	ds_read_b32 v211, v211
	ds_read_b32 v201, v201
	ds_read_b32 v212, v212
	ds_read_b32 v198, v198
	ds_read_b32 v213, v213
	ds_read_b32 v199, v199
	ds_read_b32 v214, v214
	ds_read_b32 v196, v196
	ds_read_b32 v186, v186
	s_waitcnt lgkmcnt(6)
	v_add_f32_e32 v90, v90, v220
	v_add_f32_e32 v210, v80, v210
	v_add_f32_e32 v80, v110, v200
	v_add_f32_e32 v211, v81, v211
	v_add_f32_e32 v81, v111, v201
	v_add_f32_e32 v212, v82, v212
	ds_read_b32 v218, v218
	ds_read_b32 v222, v222
	ds_read_b32 v194, v194
	ds_read_b32 v188, v188
	ds_read_b32 v190, v190
	ds_read_b32 v216, v216
	s_waitcnt lgkmcnt(6)
	v_add_f32_e32 v82, v108, v198
	v_add_f32_e32 v213, v83, v213
	v_add_f32_e32 v83, v109, v199
	v_add_f32_e32 v214, v84, v214
	v_add_f32_e32 v84, v106, v196
	v_add_f32_e32 v106, v96, v186
	ds_read_b32 v224, v224
	ds_read_b32 v192, v192
	ds_read_b32 v215, v215
	ds_read_b32 v197, v197
	ds_read_b32 v187, v187
	ds_read_b32 v193, v193
	s_waitcnt lgkmcnt(6)
	v_add_f32_e32 v96, v88, v218
	v_add_f32_e32 v88, v92, v222
	v_add_f32_e32 v92, v104, v194
	v_add_f32_e32 v104, v98, v188
	v_add_f32_e32 v98, v100, v190
	v_add_f32_e32 v100, v86, v216
	ds_read_b32 v217, v217
	ds_read_b32 v225, v225
	ds_read_b32 v219, v219
	ds_read_b32 v223, v223
	ds_read_b32 v221, v221
	ds_read_b32 v195, v195
	s_waitcnt lgkmcnt(6)
	v_add_f32_e32 v86, v94, v224
	v_add_f32_e32 v94, v102, v192
	v_add_f32_e32 v215, v85, v215
	v_add_f32_e32 v85, v107, v197
	v_add_f32_e32 v107, v97, v187
	v_add_f32_e32 v97, v103, v193
	ds_read_b32 v189, v189
	ds_read_b32 v191, v191
	s_waitcnt lgkmcnt(2)
	v_add_f32_e32 v217, v87, v217
	v_add_f32_e32 v87, v95, v225
	v_add_f32_e32 v95, v89, v219
	v_add_f32_e32 v89, v93, v223
	v_add_f32_e32 v93, v91, v221
	v_add_f32_e32 v91, v105, v195
	s_waitcnt lgkmcnt(0)
	v_add_f32_e32 v105, v99, v189
	v_add_f32_e32 v99, v101, v191
	v_mov_b32_e32 v110, v210
	v_mov_b32_e32 v111, v211
	v_mov_b32_e32 v108, v212
	v_mov_b32_e32 v109, v213
	v_mov_b32_e32 v102, v214
	v_mov_b32_e32 v103, v215
	v_mov_b32_e32 v101, v217
	s_andn2_b64 vcc, exec, s[4:5]
	s_cbranch_vccnz .LBB0_780
; template <int DQK, bool MOBA>
; __device__ __forceinline__ void attn_unit(const Args& A, int b, int h, int qb, lptr lds) {
;     ...
;             if (diag) {
; #pragma unroll
;                 for (int r = 0; r < 16; ++r) {
;                     const int kl = 64 * tt + (r & 3) + 8 * (r >> 2) + 4 * hi;
;                     if (kl > qrel) s0[r] = NEG;
;                     if (kl + 32 > qrel) s1[r] = NEG;
;                 }
;             }
	v_add_u32_e32 v186, s13, v176
	v_add_u32_e32 v187, 32, v186
	v_cmp_le_i32_e32 vcc, v186, v177
	v_cmp_le_i32_e64 s[0:1], v187, v177
	v_add_u32_e32 v187, 33, v186
	v_cndmask_b32_e32 v106, v209, v106, vcc
	v_cmp_le_i32_e32 vcc, v187, v177
	v_add_u32_e32 v187, 2, v186
	v_cndmask_b32_e64 v110, v209, v110, s[0:1]
	v_cndmask_b32_e32 v111, v209, v111, vcc
	v_cmp_le_i32_e32 vcc, v187, v177
	v_add_u32_e32 v187, 34, v186
	v_cmp_lt_i32_e64 s[0:1], v186, v177
	v_cndmask_b32_e32 v104, v209, v104, vcc
	v_cmp_le_i32_e32 vcc, v187, v177
	v_add_u32_e32 v187, 3, v186
	v_cndmask_b32_e64 v107, v209, v107, s[0:1]
	v_cndmask_b32_e32 v108, v209, v108, vcc
	v_cmp_le_i32_e32 vcc, v187, v177
	v_add_u32_e32 v187, 35, v186
	s_nop 0
	v_cndmask_b32_e32 v105, v209, v105, vcc
	v_cmp_le_i32_e32 vcc, v187, v177
	v_add_u32_e32 v187, 8, v186
	s_nop 0
	v_cndmask_b32_e32 v109, v209, v109, vcc
	v_cmp_le_i32_e32 vcc, v187, v177
	v_add_u32_e32 v187, 40, v186
	s_nop 0
	v_cndmask_b32_e32 v98, v209, v98, vcc
	v_cmp_le_i32_e32 vcc, v187, v177
	v_add_u32_e32 v187, 9, v186
	s_nop 0
	v_cndmask_b32_e32 v102, v209, v102, vcc
	v_cmp_le_i32_e32 vcc, v187, v177
	v_add_u32_e32 v187, 41, v186
	s_nop 0
	v_cndmask_b32_e32 v99, v209, v99, vcc
	v_cmp_le_i32_e32 vcc, v187, v177
	v_add_u32_e32 v187, 10, v186
	s_nop 0
	v_cndmask_b32_e32 v103, v209, v103, vcc
	v_cmp_le_i32_e32 vcc, v187, v177
	v_add_u32_e32 v187, 42, v186
	s_nop 0
	v_cndmask_b32_e32 v94, v209, v94, vcc
	v_cmp_le_i32_e32 vcc, v187, v177
	v_add_u32_e32 v187, 11, v186
	s_nop 0
	v_cndmask_b32_e32 v100, v209, v100, vcc
	v_cmp_le_i32_e32 vcc, v187, v177
	v_add_u32_e32 v187, 43, v186
	s_nop 0
	v_cndmask_b32_e32 v97, v209, v97, vcc
	v_cmp_le_i32_e32 vcc, v187, v177
	v_add_u32_e32 v187, 16, v186
	s_nop 0
	v_cndmask_b32_e32 v101, v209, v101, vcc
	v_cmp_le_i32_e32 vcc, v187, v177
	v_add_u32_e32 v187, 48, v186
	s_nop 0
	v_cndmask_b32_e32 v92, v209, v92, vcc
	v_cmp_le_i32_e32 vcc, v187, v177
	v_add_u32_e32 v187, 17, v186
	s_nop 0
	v_cndmask_b32_e32 v96, v209, v96, vcc
	v_cmp_le_i32_e32 vcc, v187, v177
	v_add_u32_e32 v187, 49, v186
	s_nop 0
	v_cndmask_b32_e32 v91, v209, v91, vcc
	v_cmp_le_i32_e32 vcc, v187, v177
	v_add_u32_e32 v187, 18, v186
	s_nop 0
	v_cndmask_b32_e32 v95, v209, v95, vcc
	v_cmp_le_i32_e32 vcc, v187, v177
	v_add_u32_e32 v187, 50, v186
	s_nop 0
	v_cndmask_b32_e32 v84, v209, v84, vcc
	v_cmp_le_i32_e32 vcc, v187, v177
	v_add_u32_e32 v187, 19, v186
	s_nop 0
	v_cndmask_b32_e32 v90, v209, v90, vcc
	v_cmp_le_i32_e32 vcc, v187, v177
	v_add_u32_e32 v187, 51, v186
	s_nop 0
	v_cndmask_b32_e32 v85, v209, v85, vcc
	v_cmp_le_i32_e32 vcc, v187, v177
	v_add_u32_e32 v187, 24, v186
	s_nop 0
	v_cndmask_b32_e32 v93, v209, v93, vcc
	v_cmp_le_i32_e32 vcc, v187, v177
	v_add_u32_e32 v187, 56, v186
	s_nop 0
	v_cndmask_b32_e32 v82, v209, v82, vcc
	v_cmp_le_i32_e32 vcc, v187, v177
	v_add_u32_e32 v187, 25, v186
	s_nop 0
	v_cndmask_b32_e32 v88, v209, v88, vcc
	v_cmp_le_i32_e32 vcc, v187, v177
	v_add_u32_e32 v187, 57, v186
	s_nop 0
	v_cndmask_b32_e32 v83, v209, v83, vcc
	v_cmp_le_i32_e32 vcc, v187, v177
	v_add_u32_e32 v187, 26, v186
	s_nop 0
	v_cndmask_b32_e32 v89, v209, v89, vcc
	v_cmp_le_i32_e32 vcc, v187, v177
	v_add_u32_e32 v187, 58, v186
	s_nop 0
	v_cndmask_b32_e32 v80, v209, v80, vcc
	v_cmp_le_i32_e32 vcc, v187, v177
	v_add_u32_e32 v187, 27, v186
	v_add_u32_e32 v186, 59, v186
	v_cndmask_b32_e32 v86, v209, v86, vcc
	v_cmp_le_i32_e32 vcc, v187, v177
	s_nop 1
	v_cndmask_b32_e32 v81, v209, v81, vcc
	v_cmp_le_i32_e32 vcc, v186, v177
	s_nop 1
	v_cndmask_b32_e32 v87, v209, v87, vcc
	s_branch .LBB0_780
